# MFMA segment hand-off trimmed: setprio raised before the pre-MFMA barrier and lowered after the post-MFMA barrier, mid-segment setprio pair and redundant lgkmcnt wait removed
# baseline (speedup 1.0000x reference)
.LBB0_328:
	s_ashr_i32 s31, s30, 31
	s_lshl_b64 s[34:35], s[30:31], 19
	s_add_u32 s34, s84, s34
	s_addc_u32 s35, s85, s35
	s_and_b64 s[38:39], s[4:5], exec
	s_cselect_b32 s7, s35, s93
	s_cselect_b32 s11, s34, s92
	s_ashr_i32 s29, s28, 31
	s_lshl_b64 s[38:39], s[28:29], 19
	s_add_u32 s38, s56, s38
	s_addc_u32 s39, s57, s39
	s_and_b64 s[46:47], s[4:5], exec
	s_cselect_b32 s0, s39, s37
	s_cselect_b32 s29, s38, s36
	s_mov_b64 s[46:47], 0
	s_mov_b32 s31, -2
	v_add_u32_e32 v224, 0x10000, v184
	s_add_u32 s50, s46, 0x100
	s_addc_u32 s51, s47, 0
	s_add_u32 s3, s46, 0xfffff900
	s_addc_u32 s33, s47, -1
	s_cmp_gt_u32 s50, 0x7ff
	s_cselect_b32 s50, s3, s50
	s_cselect_b32 s51, s33, s51
	s_add_u32 s3, s92, s50
	s_addc_u32 s33, s93, s51
	s_add_u32 s43, s36, s50
	s_addc_u32 s54, s37, s51
	s_add_i32 s69, 0, 0x10000
	s_cmp_eq_u32 s31, 12
	s_cselect_b32 s97, s7, s33
	s_cselect_b32 s96, s11, s3
	s_cselect_b32 s95, s0, s54
	s_cselect_b32 s94, s29, s43
	s_add_i32 s3, 0, 0x14000
	ds_read_b128 v[40:43], v224
	ds_read_b128 v[60:63], v224 offset:1024
	ds_read_b128 v[80:83], v224 offset:2048
	ds_read_b128 v[100:103], v224 offset:3072
	ds_read_b128 v[120:123], v224 offset:16384
	ds_read_b128 v[140:143], v224 offset:17408
	ds_read_b128 v[152:155], v224 offset:18432
	ds_read_b128 v[168:171], v224 offset:19456
	s_add_u32 s33, s92, s46
	s_addc_u32 s43, s93, s47
	s_add_u32 s46, s33, 0x40080
	s_addc_u32 s47, s43, 0
	s_add_i32 m0, s23, 0xc000
	ds_read_b128 v[172:175], v202
	ds_read_b128 v[176:179], v202 offset:1024
	ds_read_b128 v[180:183], v202 offset:2048
	ds_read_b128 v[204:207], v202 offset:3072
	ds_read_b128 v[208:211], v202 offset:4096
	ds_read_b128 v[212:215], v202 offset:5120
	ds_read_b128 v[216:219], v202 offset:6144
	ds_read_b128 v[220:223], v202 offset:7168
	global_load_lds_dwordx4 v156, s[46:47]
	s_add_i32 m0, s23, 0xe000
	s_nop 0
	global_load_lds_dwordx4 v160, s[46:47]
	s_waitcnt vmcnt(8)
	s_waitcnt lgkmcnt(0)
	s_setprio 1
	s_barrier
	v_mfma_f32_16x16x32_bf16 v[148:151], v[40:43], v[172:175], 0
	v_mfma_f32_16x16x32_bf16 v[144:147], v[80:83], v[172:175], 0
	v_mfma_f32_16x16x32_bf16 v[128:131], v[40:43], v[180:183], 0
	v_mfma_f32_16x16x32_bf16 v[124:127], v[80:83], v[180:183], 0
	v_mfma_f32_16x16x32_bf16 v[108:111], v[40:43], v[208:211], 0
	v_mfma_f32_16x16x32_bf16 v[104:107], v[80:83], v[208:211], 0
	v_mfma_f32_16x16x32_bf16 v[88:91], v[40:43], v[216:219], 0
	v_mfma_f32_16x16x32_bf16 v[84:87], v[80:83], v[216:219], 0
	v_mfma_f32_16x16x32_bf16 v[148:151], v[60:63], v[176:179], v[148:151]
	v_mfma_f32_16x16x32_bf16 v[144:147], v[100:103], v[176:179], v[144:147]
	v_mfma_f32_16x16x32_bf16 v[128:131], v[60:63], v[204:207], v[128:131]
	v_mfma_f32_16x16x32_bf16 v[124:127], v[100:103], v[204:207], v[124:127]
	v_mfma_f32_16x16x32_bf16 v[108:111], v[60:63], v[212:215], v[108:111]
	v_mfma_f32_16x16x32_bf16 v[104:107], v[100:103], v[212:215], v[104:107]
	v_mfma_f32_16x16x32_bf16 v[88:91], v[60:63], v[220:223], v[88:91]
	v_mfma_f32_16x16x32_bf16 v[84:87], v[100:103], v[220:223], v[84:87]
	v_mfma_f32_16x16x32_bf16 v[136:139], v[120:123], v[172:175], 0
	v_mfma_f32_16x16x32_bf16 v[132:135], v[152:155], v[172:175], 0
	v_mfma_f32_16x16x32_bf16 v[116:119], v[120:123], v[180:183], 0
	v_mfma_f32_16x16x32_bf16 v[112:115], v[152:155], v[180:183], 0
	v_mfma_f32_16x16x32_bf16 v[96:99], v[120:123], v[208:211], 0
	v_mfma_f32_16x16x32_bf16 v[92:95], v[152:155], v[208:211], 0
	v_mfma_f32_16x16x32_bf16 v[76:79], v[120:123], v[216:219], 0
	v_mfma_f32_16x16x32_bf16 v[72:75], v[152:155], v[216:219], 0
	v_mfma_f32_16x16x32_bf16 v[136:139], v[140:143], v[176:179], v[136:139]
	v_mfma_f32_16x16x32_bf16 v[132:135], v[168:171], v[176:179], v[132:135]
	v_mfma_f32_16x16x32_bf16 v[116:119], v[140:143], v[204:207], v[116:119]
	v_mfma_f32_16x16x32_bf16 v[112:115], v[168:171], v[204:207], v[112:115]
	v_mfma_f32_16x16x32_bf16 v[96:99], v[140:143], v[212:215], v[96:99]
	v_mfma_f32_16x16x32_bf16 v[92:95], v[168:171], v[212:215], v[92:95]
	v_mfma_f32_16x16x32_bf16 v[76:79], v[140:143], v[220:223], v[76:79]
	v_mfma_f32_16x16x32_bf16 v[72:75], v[168:171], v[220:223], v[72:75]
	s_barrier
	s_setprio 0
	s_add_i32 s33, s69, s60
	s_mov_b32 m0, s33
	ds_read_b128 v[172:175], v202 offset:16384
	ds_read_b128 v[176:179], v202 offset:17408
	ds_read_b128 v[180:183], v202 offset:18432
	ds_read_b128 v[204:207], v202 offset:19456
	ds_read_b128 v[208:211], v202 offset:20480
	ds_read_b128 v[212:215], v202 offset:21504
	ds_read_b128 v[216:219], v202 offset:22528
	ds_read_b128 v[220:223], v202 offset:23552
	global_load_lds_dwordx4 v158, s[94:95]
	s_add_i32 m0, s33, 0x2000
	s_add_u32 s46, s94, 0x40000
	s_addc_u32 s47, s95, 0
	s_add_i32 s3, s3, s60
	global_load_lds_dwordx4 v162, s[94:95]
	s_mov_b32 m0, s3
	s_nop 0
	global_load_lds_dwordx4 v158, s[46:47]
	s_add_i32 m0, s3, 0x2000
	s_nop 0
	global_load_lds_dwordx4 v162, s[46:47]
	s_mov_b32 m0, s23
	s_nop 0
	global_load_lds_dwordx4 v156, s[96:97]
	s_mov_b32 m0, s87
	s_nop 0
	global_load_lds_dwordx4 v160, s[96:97]
	s_waitcnt vmcnt(8)
	s_waitcnt lgkmcnt(0)
	s_setprio 1
	s_barrier
	v_mfma_f32_16x16x32_bf16 v[68:71], v[40:43], v[172:175], 0
	v_mfma_f32_16x16x32_bf16 v[64:67], v[80:83], v[172:175], 0
	v_mfma_f32_16x16x32_bf16 v[48:51], v[40:43], v[180:183], 0
	v_mfma_f32_16x16x32_bf16 v[44:47], v[80:83], v[180:183], 0
	v_mfma_f32_16x16x32_bf16 v[28:31], v[40:43], v[208:211], 0
	v_mfma_f32_16x16x32_bf16 v[24:27], v[80:83], v[208:211], 0
	v_mfma_f32_16x16x32_bf16 v[12:15], v[40:43], v[216:219], 0
	v_mfma_f32_16x16x32_bf16 v[8:11], v[80:83], v[216:219], 0
	v_mfma_f32_16x16x32_bf16 v[68:71], v[60:63], v[176:179], v[68:71]
	v_mfma_f32_16x16x32_bf16 v[64:67], v[100:103], v[176:179], v[64:67]
	v_mfma_f32_16x16x32_bf16 v[48:51], v[60:63], v[204:207], v[48:51]
	v_mfma_f32_16x16x32_bf16 v[44:47], v[100:103], v[204:207], v[44:47]
	v_mfma_f32_16x16x32_bf16 v[28:31], v[60:63], v[212:215], v[28:31]
	v_mfma_f32_16x16x32_bf16 v[24:27], v[100:103], v[212:215], v[24:27]
	v_mfma_f32_16x16x32_bf16 v[12:15], v[60:63], v[220:223], v[12:15]
	v_mfma_f32_16x16x32_bf16 v[8:11], v[100:103], v[220:223], v[8:11]
	v_mfma_f32_16x16x32_bf16 v[52:55], v[152:155], v[172:175], 0
	v_mfma_f32_16x16x32_bf16 v[36:39], v[120:123], v[180:183], 0
	v_mfma_f32_16x16x32_bf16 v[32:35], v[152:155], v[180:183], 0
	v_mfma_f32_16x16x32_bf16 v[20:23], v[120:123], v[208:211], 0
	v_mfma_f32_16x16x32_bf16 v[16:19], v[152:155], v[208:211], 0
	v_mfma_f32_16x16x32_bf16 v[4:7], v[120:123], v[216:219], 0
	v_mfma_f32_16x16x32_bf16 v[0:3], v[152:155], v[216:219], 0
	v_mfma_f32_16x16x32_bf16 v[40:43], v[120:123], v[172:175], 0
	v_mfma_f32_16x16x32_bf16 v[52:55], v[168:171], v[176:179], v[52:55]
	v_mfma_f32_16x16x32_bf16 v[36:39], v[140:143], v[204:207], v[36:39]
	v_mfma_f32_16x16x32_bf16 v[32:35], v[168:171], v[204:207], v[32:35]
	v_mfma_f32_16x16x32_bf16 v[20:23], v[140:143], v[212:215], v[20:23]
	v_mfma_f32_16x16x32_bf16 v[16:19], v[168:171], v[212:215], v[16:19]
	v_mfma_f32_16x16x32_bf16 v[4:7], v[140:143], v[220:223], v[4:7]
	v_mfma_f32_16x16x32_bf16 v[0:3], v[168:171], v[220:223], v[0:3]
	v_mfma_f32_16x16x32_bf16 v[40:43], v[140:143], v[176:179], v[40:43]
	s_barrier
	s_setprio 0
	s_add_i32 s3, 0, 0x18000
	s_add_i32 s33, 0, 0x1c000
	ds_read_b128 v[56:59], v224 offset:32768
	ds_read_b128 v[60:63], v224 offset:33792
	ds_read_b128 v[80:83], v224 offset:34816
	ds_read_b128 v[100:103], v224 offset:35840
	ds_read_b128 v[120:123], v224 offset:49152
	ds_read_b128 v[140:143], v224 offset:50176
	ds_read_b128 v[152:155], v224 offset:51200
	ds_read_b128 v[168:171], v224 offset:52224
	s_add_u32 s46, s96, 0x40000
	s_addc_u32 s47, s97, 0
	s_mov_b32 m0, s89
	ds_read_b128 v[172:175], v202 offset:32768
	ds_read_b128 v[176:179], v202 offset:33792
	ds_read_b128 v[180:183], v202 offset:34816
	ds_read_b128 v[204:207], v202 offset:35840
	ds_read_b128 v[208:211], v202 offset:36864
	ds_read_b128 v[212:215], v202 offset:37888
	ds_read_b128 v[216:219], v202 offset:38912
	ds_read_b128 v[220:223], v202 offset:39936
	global_load_lds_dwordx4 v156, s[46:47]
	s_mov_b32 m0, s98
	s_nop 0
	global_load_lds_dwordx4 v160, s[46:47]
	s_waitcnt vmcnt(8)
	s_waitcnt lgkmcnt(0)
	s_setprio 1
	s_barrier
	v_mfma_f32_16x16x32_bf16 v[148:151], v[56:59], v[172:175], v[148:151]
	v_mfma_f32_16x16x32_bf16 v[144:147], v[80:83], v[172:175], v[144:147]
	v_mfma_f32_16x16x32_bf16 v[128:131], v[56:59], v[180:183], v[128:131]
	v_mfma_f32_16x16x32_bf16 v[124:127], v[80:83], v[180:183], v[124:127]
	v_mfma_f32_16x16x32_bf16 v[108:111], v[56:59], v[208:211], v[108:111]
	v_mfma_f32_16x16x32_bf16 v[104:107], v[80:83], v[208:211], v[104:107]
	v_mfma_f32_16x16x32_bf16 v[88:91], v[56:59], v[216:219], v[88:91]
	v_mfma_f32_16x16x32_bf16 v[84:87], v[80:83], v[216:219], v[84:87]
	v_mfma_f32_16x16x32_bf16 v[148:151], v[60:63], v[176:179], v[148:151]
	v_mfma_f32_16x16x32_bf16 v[144:147], v[100:103], v[176:179], v[144:147]
	v_mfma_f32_16x16x32_bf16 v[128:131], v[60:63], v[204:207], v[128:131]
	v_mfma_f32_16x16x32_bf16 v[124:127], v[100:103], v[204:207], v[124:127]
	v_mfma_f32_16x16x32_bf16 v[108:111], v[60:63], v[212:215], v[108:111]
	v_mfma_f32_16x16x32_bf16 v[104:107], v[100:103], v[212:215], v[104:107]
	v_mfma_f32_16x16x32_bf16 v[88:91], v[60:63], v[220:223], v[88:91]
	v_mfma_f32_16x16x32_bf16 v[84:87], v[100:103], v[220:223], v[84:87]
	v_mfma_f32_16x16x32_bf16 v[136:139], v[120:123], v[172:175], v[136:139]
	v_mfma_f32_16x16x32_bf16 v[132:135], v[152:155], v[172:175], v[132:135]
	v_mfma_f32_16x16x32_bf16 v[116:119], v[120:123], v[180:183], v[116:119]
	v_mfma_f32_16x16x32_bf16 v[112:115], v[152:155], v[180:183], v[112:115]
	v_mfma_f32_16x16x32_bf16 v[96:99], v[120:123], v[208:211], v[96:99]
	v_mfma_f32_16x16x32_bf16 v[92:95], v[152:155], v[208:211], v[92:95]
	v_mfma_f32_16x16x32_bf16 v[76:79], v[120:123], v[216:219], v[76:79]
	v_mfma_f32_16x16x32_bf16 v[72:75], v[152:155], v[216:219], v[72:75]
	v_mfma_f32_16x16x32_bf16 v[136:139], v[140:143], v[176:179], v[136:139]
	v_mfma_f32_16x16x32_bf16 v[132:135], v[168:171], v[176:179], v[132:135]
	v_mfma_f32_16x16x32_bf16 v[116:119], v[140:143], v[204:207], v[116:119]
	v_mfma_f32_16x16x32_bf16 v[112:115], v[168:171], v[204:207], v[112:115]
	v_mfma_f32_16x16x32_bf16 v[96:99], v[140:143], v[212:215], v[96:99]
	v_mfma_f32_16x16x32_bf16 v[92:95], v[168:171], v[212:215], v[92:95]
	v_mfma_f32_16x16x32_bf16 v[76:79], v[140:143], v[220:223], v[76:79]
	v_mfma_f32_16x16x32_bf16 v[72:75], v[168:171], v[220:223], v[72:75]
	s_barrier
	s_setprio 0
	s_add_i32 s3, s3, s60
	s_add_u32 s100, s94, 0x80
	s_addc_u32 s101, s95, 0
	s_mov_b32 m0, s3
	ds_read_b128 v[172:175], v202 offset:49152
	ds_read_b128 v[176:179], v202 offset:50176
	ds_read_b128 v[180:183], v202 offset:51200
	ds_read_b128 v[204:207], v202 offset:52224
	ds_read_b128 v[208:211], v202 offset:53248
	ds_read_b128 v[212:215], v202 offset:54272
	ds_read_b128 v[216:219], v202 offset:55296
	ds_read_b128 v[220:223], v202 offset:56320
	global_load_lds_dwordx4 v158, s[100:101]
	s_add_i32 m0, s3, 0x2000
	s_add_u32 s46, s94, 0x40080
	s_addc_u32 s47, s95, 0
	s_add_i32 s3, s33, s60
	global_load_lds_dwordx4 v162, s[100:101]
	s_mov_b32 m0, s3
	s_nop 0
	global_load_lds_dwordx4 v158, s[46:47]
	s_add_i32 m0, s3, 0x2000
	s_nop 0
	global_load_lds_dwordx4 v162, s[46:47]
	s_add_u32 s100, s96, 0x80
	s_addc_u32 s101, s97, 0
	s_mov_b32 m0, s99
	s_nop 0
	global_load_lds_dwordx4 v156, s[100:101]
	s_mov_b32 m0, s16
	s_nop 0
	global_load_lds_dwordx4 v160, s[100:101]
	s_waitcnt vmcnt(8)
	s_waitcnt lgkmcnt(0)
	s_setprio 1
	s_barrier
	v_mfma_f32_16x16x32_bf16 v[68:71], v[56:59], v[172:175], v[68:71]
	v_mfma_f32_16x16x32_bf16 v[64:67], v[80:83], v[172:175], v[64:67]
	v_mfma_f32_16x16x32_bf16 v[48:51], v[56:59], v[180:183], v[48:51]
	v_mfma_f32_16x16x32_bf16 v[44:47], v[80:83], v[180:183], v[44:47]
	v_mfma_f32_16x16x32_bf16 v[28:31], v[56:59], v[208:211], v[28:31]
	v_mfma_f32_16x16x32_bf16 v[24:27], v[80:83], v[208:211], v[24:27]
	v_mfma_f32_16x16x32_bf16 v[12:15], v[56:59], v[216:219], v[12:15]
	v_mfma_f32_16x16x32_bf16 v[8:11], v[80:83], v[216:219], v[8:11]
	v_mfma_f32_16x16x32_bf16 v[68:71], v[60:63], v[176:179], v[68:71]
	v_mfma_f32_16x16x32_bf16 v[64:67], v[100:103], v[176:179], v[64:67]
	v_mfma_f32_16x16x32_bf16 v[48:51], v[60:63], v[204:207], v[48:51]
	v_mfma_f32_16x16x32_bf16 v[44:47], v[100:103], v[204:207], v[44:47]
	v_mfma_f32_16x16x32_bf16 v[28:31], v[60:63], v[212:215], v[28:31]
	v_mfma_f32_16x16x32_bf16 v[24:27], v[100:103], v[212:215], v[24:27]
	v_mfma_f32_16x16x32_bf16 v[12:15], v[60:63], v[220:223], v[12:15]
	v_mfma_f32_16x16x32_bf16 v[8:11], v[100:103], v[220:223], v[8:11]
	v_mfma_f32_16x16x32_bf16 v[40:43], v[120:123], v[172:175], v[40:43]
	v_mfma_f32_16x16x32_bf16 v[56:59], v[140:143], v[176:179], v[40:43]
	v_mfma_f32_16x16x32_bf16 v[40:43], v[152:155], v[172:175], v[52:55]
	v_mfma_f32_16x16x32_bf16 v[36:39], v[120:123], v[180:183], v[36:39]
	v_mfma_f32_16x16x32_bf16 v[32:35], v[152:155], v[180:183], v[32:35]
	v_mfma_f32_16x16x32_bf16 v[20:23], v[120:123], v[208:211], v[20:23]
	v_mfma_f32_16x16x32_bf16 v[16:19], v[152:155], v[208:211], v[16:19]
	v_mfma_f32_16x16x32_bf16 v[4:7], v[120:123], v[216:219], v[4:7]
	v_mfma_f32_16x16x32_bf16 v[0:3], v[152:155], v[216:219], v[0:3]
	v_mfma_f32_16x16x32_bf16 v[52:55], v[168:171], v[176:179], v[40:43]
	v_mfma_f32_16x16x32_bf16 v[36:39], v[140:143], v[204:207], v[36:39]
	v_mfma_f32_16x16x32_bf16 v[32:35], v[168:171], v[204:207], v[32:35]
	v_mfma_f32_16x16x32_bf16 v[20:23], v[140:143], v[212:215], v[20:23]
	v_mfma_f32_16x16x32_bf16 v[16:19], v[168:171], v[212:215], v[16:19]
	v_mfma_f32_16x16x32_bf16 v[4:7], v[140:143], v[220:223], v[4:7]
	v_mfma_f32_16x16x32_bf16 v[0:3], v[168:171], v[220:223], v[0:3]
	s_barrier
	s_setprio 0
	s_add_i32 s31, s31, 2
	s_cmp_gt_u32 s31, 13
	s_mov_b64 s[46:47], s[50:51]
	s_cbranch_scc1 .Lpeel_exit_mixin
.LBB0_329:
	s_add_u32 s50, s46, 0x100
	s_addc_u32 s51, s47, 0
	s_add_u32 s3, s46, 0xfffff900
	s_addc_u32 s33, s47, -1
	s_cmp_gt_u32 s50, 0x7ff
	s_cselect_b32 s50, s3, s50
	s_cselect_b32 s51, s33, s51
	s_add_u32 s3, s92, s50
	s_addc_u32 s33, s93, s51
	s_add_u32 s43, s36, s50
	s_addc_u32 s54, s37, s51
	s_add_i32 s69, 0, 0x10000
	s_cmp_eq_u32 s31, 12
	s_cselect_b32 s97, s7, s33
	s_cselect_b32 s96, s11, s3
	s_cselect_b32 s95, s0, s54
	s_cselect_b32 s94, s29, s43
	s_add_i32 s3, 0, 0x14000
	ds_read_b128 v[40:43], v224
	ds_read_b128 v[60:63], v224 offset:1024
	ds_read_b128 v[80:83], v224 offset:2048
	ds_read_b128 v[100:103], v224 offset:3072
	ds_read_b128 v[120:123], v224 offset:16384
	ds_read_b128 v[140:143], v224 offset:17408
	ds_read_b128 v[152:155], v224 offset:18432
	ds_read_b128 v[168:171], v224 offset:19456
	s_add_u32 s33, s92, s46
	s_addc_u32 s43, s93, s47
	s_add_u32 s46, s33, 0x40080
	s_addc_u32 s47, s43, 0
	s_add_i32 m0, s23, 0xc000
	ds_read_b128 v[172:175], v202
	ds_read_b128 v[176:179], v202 offset:1024
	ds_read_b128 v[180:183], v202 offset:2048
	ds_read_b128 v[204:207], v202 offset:3072
	ds_read_b128 v[208:211], v202 offset:4096
	ds_read_b128 v[212:215], v202 offset:5120
	ds_read_b128 v[216:219], v202 offset:6144
	ds_read_b128 v[220:223], v202 offset:7168
	global_load_lds_dwordx4 v156, s[46:47]
	s_add_i32 m0, s23, 0xe000
	s_nop 0
	global_load_lds_dwordx4 v160, s[46:47]
	s_waitcnt vmcnt(8)
	s_waitcnt lgkmcnt(0)
	s_setprio 1
	s_barrier
	v_mfma_f32_16x16x32_bf16 v[148:151], v[40:43], v[172:175], v[148:151]
	v_mfma_f32_16x16x32_bf16 v[144:147], v[80:83], v[172:175], v[144:147]
	v_mfma_f32_16x16x32_bf16 v[128:131], v[40:43], v[180:183], v[128:131]
	v_mfma_f32_16x16x32_bf16 v[124:127], v[80:83], v[180:183], v[124:127]
	v_mfma_f32_16x16x32_bf16 v[108:111], v[40:43], v[208:211], v[108:111]
	v_mfma_f32_16x16x32_bf16 v[104:107], v[80:83], v[208:211], v[104:107]
	v_mfma_f32_16x16x32_bf16 v[88:91], v[40:43], v[216:219], v[88:91]
	v_mfma_f32_16x16x32_bf16 v[84:87], v[80:83], v[216:219], v[84:87]
	v_mfma_f32_16x16x32_bf16 v[148:151], v[60:63], v[176:179], v[148:151]
	v_mfma_f32_16x16x32_bf16 v[144:147], v[100:103], v[176:179], v[144:147]
	v_mfma_f32_16x16x32_bf16 v[128:131], v[60:63], v[204:207], v[128:131]
	v_mfma_f32_16x16x32_bf16 v[124:127], v[100:103], v[204:207], v[124:127]
	v_mfma_f32_16x16x32_bf16 v[108:111], v[60:63], v[212:215], v[108:111]
	v_mfma_f32_16x16x32_bf16 v[104:107], v[100:103], v[212:215], v[104:107]
	v_mfma_f32_16x16x32_bf16 v[88:91], v[60:63], v[220:223], v[88:91]
	v_mfma_f32_16x16x32_bf16 v[84:87], v[100:103], v[220:223], v[84:87]
	v_mfma_f32_16x16x32_bf16 v[136:139], v[120:123], v[172:175], v[136:139]
	v_mfma_f32_16x16x32_bf16 v[132:135], v[152:155], v[172:175], v[132:135]
	v_mfma_f32_16x16x32_bf16 v[116:119], v[120:123], v[180:183], v[116:119]
	v_mfma_f32_16x16x32_bf16 v[112:115], v[152:155], v[180:183], v[112:115]
	v_mfma_f32_16x16x32_bf16 v[96:99], v[120:123], v[208:211], v[96:99]
	v_mfma_f32_16x16x32_bf16 v[92:95], v[152:155], v[208:211], v[92:95]
	v_mfma_f32_16x16x32_bf16 v[76:79], v[120:123], v[216:219], v[76:79]
	v_mfma_f32_16x16x32_bf16 v[72:75], v[152:155], v[216:219], v[72:75]
	v_mfma_f32_16x16x32_bf16 v[136:139], v[140:143], v[176:179], v[136:139]
	v_mfma_f32_16x16x32_bf16 v[132:135], v[168:171], v[176:179], v[132:135]
	v_mfma_f32_16x16x32_bf16 v[116:119], v[140:143], v[204:207], v[116:119]
	v_mfma_f32_16x16x32_bf16 v[112:115], v[168:171], v[204:207], v[112:115]
	v_mfma_f32_16x16x32_bf16 v[96:99], v[140:143], v[212:215], v[96:99]
	v_mfma_f32_16x16x32_bf16 v[92:95], v[168:171], v[212:215], v[92:95]
	v_mfma_f32_16x16x32_bf16 v[76:79], v[140:143], v[220:223], v[76:79]
	v_mfma_f32_16x16x32_bf16 v[72:75], v[168:171], v[220:223], v[72:75]
	s_barrier
	s_setprio 0
	s_add_i32 s33, s69, s60
	s_mov_b32 m0, s33
	ds_read_b128 v[172:175], v202 offset:16384
	ds_read_b128 v[176:179], v202 offset:17408
	ds_read_b128 v[180:183], v202 offset:18432
	ds_read_b128 v[204:207], v202 offset:19456
	ds_read_b128 v[208:211], v202 offset:20480
	ds_read_b128 v[212:215], v202 offset:21504
	ds_read_b128 v[216:219], v202 offset:22528
	ds_read_b128 v[220:223], v202 offset:23552
	global_load_lds_dwordx4 v158, s[94:95]
	s_add_i32 m0, s33, 0x2000
	s_add_u32 s46, s94, 0x40000
	s_addc_u32 s47, s95, 0
	s_add_i32 s3, s3, s60
	global_load_lds_dwordx4 v162, s[94:95]
	s_mov_b32 m0, s3
	s_nop 0
	global_load_lds_dwordx4 v158, s[46:47]
	s_add_i32 m0, s3, 0x2000
	s_nop 0
	global_load_lds_dwordx4 v162, s[46:47]
	s_mov_b32 m0, s23
	s_nop 0
	global_load_lds_dwordx4 v156, s[96:97]
	s_mov_b32 m0, s87
	s_nop 0
	global_load_lds_dwordx4 v160, s[96:97]
	s_waitcnt vmcnt(8)
	s_waitcnt lgkmcnt(0)
	s_setprio 1
	s_barrier
	v_mfma_f32_16x16x32_bf16 v[68:71], v[40:43], v[172:175], v[68:71]
	v_mfma_f32_16x16x32_bf16 v[64:67], v[80:83], v[172:175], v[64:67]
	v_mfma_f32_16x16x32_bf16 v[48:51], v[40:43], v[180:183], v[48:51]
	v_mfma_f32_16x16x32_bf16 v[44:47], v[80:83], v[180:183], v[44:47]
	v_mfma_f32_16x16x32_bf16 v[28:31], v[40:43], v[208:211], v[28:31]
	v_mfma_f32_16x16x32_bf16 v[24:27], v[80:83], v[208:211], v[24:27]
	v_mfma_f32_16x16x32_bf16 v[12:15], v[40:43], v[216:219], v[12:15]
	v_mfma_f32_16x16x32_bf16 v[8:11], v[80:83], v[216:219], v[8:11]
	v_mfma_f32_16x16x32_bf16 v[68:71], v[60:63], v[176:179], v[68:71]
	v_mfma_f32_16x16x32_bf16 v[64:67], v[100:103], v[176:179], v[64:67]
	v_mfma_f32_16x16x32_bf16 v[48:51], v[60:63], v[204:207], v[48:51]
	v_mfma_f32_16x16x32_bf16 v[44:47], v[100:103], v[204:207], v[44:47]
	v_mfma_f32_16x16x32_bf16 v[28:31], v[60:63], v[212:215], v[28:31]
	v_mfma_f32_16x16x32_bf16 v[24:27], v[100:103], v[212:215], v[24:27]
	v_mfma_f32_16x16x32_bf16 v[12:15], v[60:63], v[220:223], v[12:15]
	v_mfma_f32_16x16x32_bf16 v[8:11], v[100:103], v[220:223], v[8:11]
	v_mfma_f32_16x16x32_bf16 v[52:55], v[152:155], v[172:175], v[52:55]
	v_mfma_f32_16x16x32_bf16 v[36:39], v[120:123], v[180:183], v[36:39]
	v_mfma_f32_16x16x32_bf16 v[32:35], v[152:155], v[180:183], v[32:35]
	v_mfma_f32_16x16x32_bf16 v[20:23], v[120:123], v[208:211], v[20:23]
	v_mfma_f32_16x16x32_bf16 v[16:19], v[152:155], v[208:211], v[16:19]
	v_mfma_f32_16x16x32_bf16 v[4:7], v[120:123], v[216:219], v[4:7]
	v_mfma_f32_16x16x32_bf16 v[0:3], v[152:155], v[216:219], v[0:3]
	v_mfma_f32_16x16x32_bf16 v[40:43], v[120:123], v[172:175], v[56:59]
	v_mfma_f32_16x16x32_bf16 v[52:55], v[168:171], v[176:179], v[52:55]
	v_mfma_f32_16x16x32_bf16 v[36:39], v[140:143], v[204:207], v[36:39]
	v_mfma_f32_16x16x32_bf16 v[32:35], v[168:171], v[204:207], v[32:35]
	v_mfma_f32_16x16x32_bf16 v[20:23], v[140:143], v[212:215], v[20:23]
	v_mfma_f32_16x16x32_bf16 v[16:19], v[168:171], v[212:215], v[16:19]
	v_mfma_f32_16x16x32_bf16 v[4:7], v[140:143], v[220:223], v[4:7]
	v_mfma_f32_16x16x32_bf16 v[0:3], v[168:171], v[220:223], v[0:3]
	v_mfma_f32_16x16x32_bf16 v[40:43], v[140:143], v[176:179], v[40:43]
	s_barrier
	s_setprio 0
	s_add_i32 s3, 0, 0x18000
	s_add_i32 s33, 0, 0x1c000
	ds_read_b128 v[56:59], v224 offset:32768
	ds_read_b128 v[60:63], v224 offset:33792
	ds_read_b128 v[80:83], v224 offset:34816
	ds_read_b128 v[100:103], v224 offset:35840
	ds_read_b128 v[120:123], v224 offset:49152
	ds_read_b128 v[140:143], v224 offset:50176
	ds_read_b128 v[152:155], v224 offset:51200
	ds_read_b128 v[168:171], v224 offset:52224
	s_add_u32 s46, s96, 0x40000
	s_addc_u32 s47, s97, 0
	s_mov_b32 m0, s89
	ds_read_b128 v[172:175], v202 offset:32768
	ds_read_b128 v[176:179], v202 offset:33792
	ds_read_b128 v[180:183], v202 offset:34816
	ds_read_b128 v[204:207], v202 offset:35840
	ds_read_b128 v[208:211], v202 offset:36864
	ds_read_b128 v[212:215], v202 offset:37888
	ds_read_b128 v[216:219], v202 offset:38912
	ds_read_b128 v[220:223], v202 offset:39936
	global_load_lds_dwordx4 v156, s[46:47]
	s_mov_b32 m0, s98
	s_nop 0
	global_load_lds_dwordx4 v160, s[46:47]
	s_waitcnt vmcnt(8)
	s_waitcnt lgkmcnt(0)
	s_setprio 1
	s_barrier
	v_mfma_f32_16x16x32_bf16 v[148:151], v[56:59], v[172:175], v[148:151]
	v_mfma_f32_16x16x32_bf16 v[144:147], v[80:83], v[172:175], v[144:147]
	v_mfma_f32_16x16x32_bf16 v[128:131], v[56:59], v[180:183], v[128:131]
	v_mfma_f32_16x16x32_bf16 v[124:127], v[80:83], v[180:183], v[124:127]
	v_mfma_f32_16x16x32_bf16 v[108:111], v[56:59], v[208:211], v[108:111]
	v_mfma_f32_16x16x32_bf16 v[104:107], v[80:83], v[208:211], v[104:107]
	v_mfma_f32_16x16x32_bf16 v[88:91], v[56:59], v[216:219], v[88:91]
	v_mfma_f32_16x16x32_bf16 v[84:87], v[80:83], v[216:219], v[84:87]
	v_mfma_f32_16x16x32_bf16 v[148:151], v[60:63], v[176:179], v[148:151]
	v_mfma_f32_16x16x32_bf16 v[144:147], v[100:103], v[176:179], v[144:147]
	v_mfma_f32_16x16x32_bf16 v[128:131], v[60:63], v[204:207], v[128:131]
	v_mfma_f32_16x16x32_bf16 v[124:127], v[100:103], v[204:207], v[124:127]
	v_mfma_f32_16x16x32_bf16 v[108:111], v[60:63], v[212:215], v[108:111]
	v_mfma_f32_16x16x32_bf16 v[104:107], v[100:103], v[212:215], v[104:107]
	v_mfma_f32_16x16x32_bf16 v[88:91], v[60:63], v[220:223], v[88:91]
	v_mfma_f32_16x16x32_bf16 v[84:87], v[100:103], v[220:223], v[84:87]
	v_mfma_f32_16x16x32_bf16 v[136:139], v[120:123], v[172:175], v[136:139]
	v_mfma_f32_16x16x32_bf16 v[132:135], v[152:155], v[172:175], v[132:135]
	v_mfma_f32_16x16x32_bf16 v[116:119], v[120:123], v[180:183], v[116:119]
	v_mfma_f32_16x16x32_bf16 v[112:115], v[152:155], v[180:183], v[112:115]
	v_mfma_f32_16x16x32_bf16 v[96:99], v[120:123], v[208:211], v[96:99]
	v_mfma_f32_16x16x32_bf16 v[92:95], v[152:155], v[208:211], v[92:95]
	v_mfma_f32_16x16x32_bf16 v[76:79], v[120:123], v[216:219], v[76:79]
	v_mfma_f32_16x16x32_bf16 v[72:75], v[152:155], v[216:219], v[72:75]
	v_mfma_f32_16x16x32_bf16 v[136:139], v[140:143], v[176:179], v[136:139]
	v_mfma_f32_16x16x32_bf16 v[132:135], v[168:171], v[176:179], v[132:135]
	v_mfma_f32_16x16x32_bf16 v[116:119], v[140:143], v[204:207], v[116:119]
	v_mfma_f32_16x16x32_bf16 v[112:115], v[168:171], v[204:207], v[112:115]
	v_mfma_f32_16x16x32_bf16 v[96:99], v[140:143], v[212:215], v[96:99]
	v_mfma_f32_16x16x32_bf16 v[92:95], v[168:171], v[212:215], v[92:95]
	v_mfma_f32_16x16x32_bf16 v[76:79], v[140:143], v[220:223], v[76:79]
	v_mfma_f32_16x16x32_bf16 v[72:75], v[168:171], v[220:223], v[72:75]
	s_barrier
	s_setprio 0
	s_add_i32 s3, s3, s60
	s_add_u32 s100, s94, 0x80
	s_addc_u32 s101, s95, 0
	s_mov_b32 m0, s3
	ds_read_b128 v[172:175], v202 offset:49152
	ds_read_b128 v[176:179], v202 offset:50176
	ds_read_b128 v[180:183], v202 offset:51200
	ds_read_b128 v[204:207], v202 offset:52224
	ds_read_b128 v[208:211], v202 offset:53248
	ds_read_b128 v[212:215], v202 offset:54272
	ds_read_b128 v[216:219], v202 offset:55296
	ds_read_b128 v[220:223], v202 offset:56320
	global_load_lds_dwordx4 v158, s[100:101]
	s_add_i32 m0, s3, 0x2000
	s_add_u32 s46, s94, 0x40080
	s_addc_u32 s47, s95, 0
	s_add_i32 s3, s33, s60
	global_load_lds_dwordx4 v162, s[100:101]
	s_mov_b32 m0, s3
	s_nop 0
	global_load_lds_dwordx4 v158, s[46:47]
	s_add_i32 m0, s3, 0x2000
	s_nop 0
	global_load_lds_dwordx4 v162, s[46:47]
	s_add_u32 s100, s96, 0x80
	s_addc_u32 s101, s97, 0
	s_mov_b32 m0, s99
	s_nop 0
	global_load_lds_dwordx4 v156, s[100:101]
	s_mov_b32 m0, s16
	s_nop 0
	global_load_lds_dwordx4 v160, s[100:101]
	s_waitcnt vmcnt(8)
	s_waitcnt lgkmcnt(0)
	s_setprio 1
	s_barrier
	v_mfma_f32_16x16x32_bf16 v[68:71], v[56:59], v[172:175], v[68:71]
	v_mfma_f32_16x16x32_bf16 v[64:67], v[80:83], v[172:175], v[64:67]
	v_mfma_f32_16x16x32_bf16 v[48:51], v[56:59], v[180:183], v[48:51]
	v_mfma_f32_16x16x32_bf16 v[44:47], v[80:83], v[180:183], v[44:47]
	v_mfma_f32_16x16x32_bf16 v[28:31], v[56:59], v[208:211], v[28:31]
	v_mfma_f32_16x16x32_bf16 v[24:27], v[80:83], v[208:211], v[24:27]
	v_mfma_f32_16x16x32_bf16 v[12:15], v[56:59], v[216:219], v[12:15]
	v_mfma_f32_16x16x32_bf16 v[8:11], v[80:83], v[216:219], v[8:11]
	v_mfma_f32_16x16x32_bf16 v[68:71], v[60:63], v[176:179], v[68:71]
	v_mfma_f32_16x16x32_bf16 v[64:67], v[100:103], v[176:179], v[64:67]
	v_mfma_f32_16x16x32_bf16 v[48:51], v[60:63], v[204:207], v[48:51]
	v_mfma_f32_16x16x32_bf16 v[44:47], v[100:103], v[204:207], v[44:47]
	v_mfma_f32_16x16x32_bf16 v[28:31], v[60:63], v[212:215], v[28:31]
	v_mfma_f32_16x16x32_bf16 v[24:27], v[100:103], v[212:215], v[24:27]
	v_mfma_f32_16x16x32_bf16 v[12:15], v[60:63], v[220:223], v[12:15]
	v_mfma_f32_16x16x32_bf16 v[8:11], v[100:103], v[220:223], v[8:11]
	v_mfma_f32_16x16x32_bf16 v[40:43], v[120:123], v[172:175], v[40:43]
	v_mfma_f32_16x16x32_bf16 v[56:59], v[140:143], v[176:179], v[40:43]
	v_mfma_f32_16x16x32_bf16 v[40:43], v[152:155], v[172:175], v[52:55]
	v_mfma_f32_16x16x32_bf16 v[36:39], v[120:123], v[180:183], v[36:39]
	v_mfma_f32_16x16x32_bf16 v[32:35], v[152:155], v[180:183], v[32:35]
	v_mfma_f32_16x16x32_bf16 v[20:23], v[120:123], v[208:211], v[20:23]
	v_mfma_f32_16x16x32_bf16 v[16:19], v[152:155], v[208:211], v[16:19]
	v_mfma_f32_16x16x32_bf16 v[4:7], v[120:123], v[216:219], v[4:7]
	v_mfma_f32_16x16x32_bf16 v[0:3], v[152:155], v[216:219], v[0:3]
	v_mfma_f32_16x16x32_bf16 v[52:55], v[168:171], v[176:179], v[40:43]
	v_mfma_f32_16x16x32_bf16 v[36:39], v[140:143], v[204:207], v[36:39]
	v_mfma_f32_16x16x32_bf16 v[32:35], v[168:171], v[204:207], v[32:35]
	v_mfma_f32_16x16x32_bf16 v[20:23], v[140:143], v[212:215], v[20:23]
	v_mfma_f32_16x16x32_bf16 v[16:19], v[168:171], v[212:215], v[16:19]
	v_mfma_f32_16x16x32_bf16 v[4:7], v[140:143], v[220:223], v[4:7]
	v_mfma_f32_16x16x32_bf16 v[0:3], v[168:171], v[220:223], v[0:3]
	s_barrier
	s_setprio 0
	s_add_i32 s31, s31, 2
	s_cmp_gt_u32 s31, 13
	s_mov_b64 s[46:47], s[50:51]
	s_cbranch_scc0 .LBB0_329

.LBB0_489:
	s_add_u32 s0, s34, s92
	s_addc_u32 s43, s35, 0
	s_mov_b64 s[36:37], 0
	s_mov_b32 s86, 0
	v_add_u32_e32 v212, 0x10000, v234
	s_add_u32 s38, s36, 0x100
	s_addc_u32 s39, s37, 0
	s_cmp_ge_u32 s38, s24
	s_cselect_b32 s47, s24, 0
	s_cselect_b32 s46, 0, 0
	s_sub_u32 s38, s38, s47
	s_subb_u32 s39, s39, s46
	s_sub_u32 s47, s36, s47
	s_subb_u32 s46, s37, s46
	s_add_u32 vcc_lo, s34, s47
	s_addc_u32 vcc_hi, s35, s46
	s_add_u32 vcc_lo, vcc_lo, 0x100
	s_addc_u32 vcc_hi, vcc_hi, 0
	s_add_u32 s47, s30, s47
	s_addc_u32 s46, s31, s46
	s_add_u32 s69, s47, 0x100
	s_addc_u32 s3, s46, 0
	s_add_i32 s33, 0, 0x10000
	s_cmp_eq_u32 s99, s86
	s_cselect_b32 s47, s11, vcc_hi
	s_cselect_b32 s46, s10, vcc_lo
	s_cselect_b32 vcc_hi, s29, s3
	s_cselect_b32 vcc_lo, s28, s69
	s_add_i32 s3, 0, 0x14000
	ds_read_b128 v[120:123], v212
	ds_read_b128 v[124:127], v212 offset:1024
	ds_read_b128 v[128:131], v212 offset:2048
	ds_read_b128 v[132:135], v212 offset:3072
	ds_read_b128 v[136:139], v212 offset:16384
	ds_read_b128 v[140:143], v212 offset:17408
	ds_read_b128 v[144:147], v212 offset:18432
	ds_read_b128 v[148:151], v212 offset:19456
	s_add_u32 s36, s0, s36
	s_addc_u32 s37, s43, s37
	s_add_u32 s100, s36, 0x80
	s_addc_u32 s101, s37, 0
	s_add_i32 m0, s94, 0xc000
	ds_read_b128 v[152:155], v248
	ds_read_b128 v[156:159], v248 offset:1024
	ds_read_b128 v[160:163], v248 offset:2048
	ds_read_b128 v[172:175], v248 offset:3072
	ds_read_b128 v[176:179], v248 offset:4096
	ds_read_b128 v[180:183], v248 offset:5120
	ds_read_b128 v[184:187], v248 offset:6144
	ds_read_b128 v[208:211], v248 offset:7168
	global_load_lds_dwordx4 v202, s[100:101]
	s_add_i32 m0, s94, 0xe000
	s_nop 0
	global_load_lds_dwordx4 v204, s[100:101]
	s_waitcnt vmcnt(8)
	s_waitcnt lgkmcnt(0)
	s_setprio 1
	s_barrier
	v_mfma_f32_16x16x32_bf16 v[168:171], v[120:123], v[152:155], 0
	v_mfma_f32_16x16x32_bf16 v[164:167], v[128:131], v[152:155], 0
	v_mfma_f32_16x16x32_bf16 v[108:111], v[120:123], v[160:163], 0
	v_mfma_f32_16x16x32_bf16 v[104:107], v[128:131], v[160:163], 0
	v_mfma_f32_16x16x32_bf16 v[92:95], v[120:123], v[176:179], 0
	v_mfma_f32_16x16x32_bf16 v[88:91], v[128:131], v[176:179], 0
	v_mfma_f32_16x16x32_bf16 v[76:79], v[120:123], v[184:187], 0
	v_mfma_f32_16x16x32_bf16 v[72:75], v[128:131], v[184:187], 0
	v_mfma_f32_16x16x32_bf16 v[168:171], v[124:127], v[156:159], v[168:171]
	v_mfma_f32_16x16x32_bf16 v[164:167], v[132:135], v[156:159], v[164:167]
	v_mfma_f32_16x16x32_bf16 v[108:111], v[124:127], v[172:175], v[108:111]
	v_mfma_f32_16x16x32_bf16 v[104:107], v[132:135], v[172:175], v[104:107]
	v_mfma_f32_16x16x32_bf16 v[92:95], v[124:127], v[180:183], v[92:95]
	v_mfma_f32_16x16x32_bf16 v[88:91], v[132:135], v[180:183], v[88:91]
	v_mfma_f32_16x16x32_bf16 v[76:79], v[124:127], v[208:211], v[76:79]
	v_mfma_f32_16x16x32_bf16 v[72:75], v[132:135], v[208:211], v[72:75]
	v_mfma_f32_16x16x32_bf16 v[116:119], v[136:139], v[152:155], 0
	v_mfma_f32_16x16x32_bf16 v[112:115], v[144:147], v[152:155], 0
	v_mfma_f32_16x16x32_bf16 v[100:103], v[136:139], v[160:163], 0
	v_mfma_f32_16x16x32_bf16 v[96:99], v[144:147], v[160:163], 0
	v_mfma_f32_16x16x32_bf16 v[84:87], v[136:139], v[176:179], 0
	v_mfma_f32_16x16x32_bf16 v[80:83], v[144:147], v[176:179], 0
	v_mfma_f32_16x16x32_bf16 v[68:71], v[136:139], v[184:187], 0
	v_mfma_f32_16x16x32_bf16 v[64:67], v[144:147], v[184:187], 0
	v_mfma_f32_16x16x32_bf16 v[116:119], v[140:143], v[156:159], v[116:119]
	v_mfma_f32_16x16x32_bf16 v[112:115], v[148:151], v[156:159], v[112:115]
	v_mfma_f32_16x16x32_bf16 v[100:103], v[140:143], v[172:175], v[100:103]
	v_mfma_f32_16x16x32_bf16 v[96:99], v[148:151], v[172:175], v[96:99]
	v_mfma_f32_16x16x32_bf16 v[84:87], v[140:143], v[180:183], v[84:87]
	v_mfma_f32_16x16x32_bf16 v[80:83], v[148:151], v[180:183], v[80:83]
	v_mfma_f32_16x16x32_bf16 v[68:71], v[140:143], v[208:211], v[68:71]
	v_mfma_f32_16x16x32_bf16 v[64:67], v[148:151], v[208:211], v[64:67]
	s_barrier
	s_setprio 0
	s_add_i32 s33, s33, s89
	s_mov_b64 s[100:101], vcc
	s_mov_b32 m0, s33
	ds_read_b128 v[152:155], v248 offset:16384
	ds_read_b128 v[156:159], v248 offset:17408
	ds_read_b128 v[160:163], v248 offset:18432
	ds_read_b128 v[172:175], v248 offset:19456
	ds_read_b128 v[176:179], v248 offset:20480
	ds_read_b128 v[180:183], v248 offset:21504
	ds_read_b128 v[184:187], v248 offset:22528
	ds_read_b128 v[208:211], v248 offset:23552
	global_load_lds_dwordx4 v188, s[100:101]
	s_add_i32 m0, s33, 0x2000
	s_add_u32 s36, vcc_lo, s92
	s_addc_u32 s37, vcc_hi, 0
	s_add_i32 s3, s3, s89
	global_load_lds_dwordx4 v206, s[100:101]
	s_mov_b32 m0, s3
	s_nop 0
	global_load_lds_dwordx4 v188, s[36:37]
	s_add_i32 m0, s3, 0x2000
	s_nop 0
	global_load_lds_dwordx4 v206, s[36:37]
	s_mov_b32 m0, s94
	s_nop 0
	global_load_lds_dwordx4 v202, s[46:47]
	s_mov_b32 m0, s95
	s_nop 0
	global_load_lds_dwordx4 v204, s[46:47]
	s_waitcnt vmcnt(8)
	s_waitcnt lgkmcnt(0)
	s_setprio 1
	s_barrier
	v_mfma_f32_16x16x32_bf16 v[60:63], v[120:123], v[152:155], 0
	v_mfma_f32_16x16x32_bf16 v[56:59], v[128:131], v[152:155], 0
	v_mfma_f32_16x16x32_bf16 v[44:47], v[120:123], v[160:163], 0
	v_mfma_f32_16x16x32_bf16 v[40:43], v[128:131], v[160:163], 0
	v_mfma_f32_16x16x32_bf16 v[28:31], v[120:123], v[176:179], 0
	v_mfma_f32_16x16x32_bf16 v[24:27], v[128:131], v[176:179], 0
	v_mfma_f32_16x16x32_bf16 v[12:15], v[120:123], v[184:187], 0
	v_mfma_f32_16x16x32_bf16 v[8:11], v[128:131], v[184:187], 0
	v_mfma_f32_16x16x32_bf16 v[60:63], v[124:127], v[156:159], v[60:63]
	v_mfma_f32_16x16x32_bf16 v[56:59], v[132:135], v[156:159], v[56:59]
	v_mfma_f32_16x16x32_bf16 v[44:47], v[124:127], v[172:175], v[44:47]
	v_mfma_f32_16x16x32_bf16 v[40:43], v[132:135], v[172:175], v[40:43]
	v_mfma_f32_16x16x32_bf16 v[28:31], v[124:127], v[180:183], v[28:31]
	v_mfma_f32_16x16x32_bf16 v[24:27], v[132:135], v[180:183], v[24:27]
	v_mfma_f32_16x16x32_bf16 v[12:15], v[124:127], v[208:211], v[12:15]
	v_mfma_f32_16x16x32_bf16 v[8:11], v[132:135], v[208:211], v[8:11]
	v_mfma_f32_16x16x32_bf16 v[52:55], v[136:139], v[152:155], 0
	v_mfma_f32_16x16x32_bf16 v[48:51], v[144:147], v[152:155], 0
	v_mfma_f32_16x16x32_bf16 v[36:39], v[136:139], v[160:163], 0
	v_mfma_f32_16x16x32_bf16 v[32:35], v[144:147], v[160:163], 0
	v_mfma_f32_16x16x32_bf16 v[20:23], v[136:139], v[176:179], 0
	v_mfma_f32_16x16x32_bf16 v[16:19], v[144:147], v[176:179], 0
	v_mfma_f32_16x16x32_bf16 v[4:7], v[136:139], v[184:187], 0
	v_mfma_f32_16x16x32_bf16 v[0:3], v[144:147], v[184:187], 0
	v_mfma_f32_16x16x32_bf16 v[52:55], v[140:143], v[156:159], v[52:55]
	v_mfma_f32_16x16x32_bf16 v[48:51], v[148:151], v[156:159], v[48:51]
	v_mfma_f32_16x16x32_bf16 v[36:39], v[140:143], v[172:175], v[36:39]
	v_mfma_f32_16x16x32_bf16 v[32:35], v[148:151], v[172:175], v[32:35]
	v_mfma_f32_16x16x32_bf16 v[20:23], v[140:143], v[180:183], v[20:23]
	v_mfma_f32_16x16x32_bf16 v[16:19], v[148:151], v[180:183], v[16:19]
	v_mfma_f32_16x16x32_bf16 v[4:7], v[140:143], v[208:211], v[4:7]
	v_mfma_f32_16x16x32_bf16 v[0:3], v[148:151], v[208:211], v[0:3]
	s_barrier
	s_setprio 0
	s_add_i32 s3, 0, 0x18000
	s_add_i32 s33, 0, 0x1c000
	ds_read_b128 v[120:123], v212 offset:32768
	ds_read_b128 v[124:127], v212 offset:33792
	ds_read_b128 v[128:131], v212 offset:34816
	ds_read_b128 v[132:135], v212 offset:35840
	ds_read_b128 v[136:139], v212 offset:49152
	ds_read_b128 v[140:143], v212 offset:50176
	ds_read_b128 v[144:147], v212 offset:51200
	ds_read_b128 v[148:151], v212 offset:52224
	s_add_u32 s36, s46, s92
	s_addc_u32 s37, s47, 0
	s_mov_b32 m0, s96
	ds_read_b128 v[152:155], v248 offset:32768
	ds_read_b128 v[156:159], v248 offset:33792
	ds_read_b128 v[160:163], v248 offset:34816
	ds_read_b128 v[172:175], v248 offset:35840
	ds_read_b128 v[176:179], v248 offset:36864
	ds_read_b128 v[180:183], v248 offset:37888
	ds_read_b128 v[184:187], v248 offset:38912
	ds_read_b128 v[208:211], v248 offset:39936
	global_load_lds_dwordx4 v202, s[36:37]
	s_mov_b32 m0, s97
	s_nop 0
	global_load_lds_dwordx4 v204, s[36:37]
	s_waitcnt vmcnt(8)
	s_waitcnt lgkmcnt(0)
	s_setprio 1
	s_barrier
	v_mfma_f32_16x16x32_bf16 v[168:171], v[120:123], v[152:155], v[168:171]
	v_mfma_f32_16x16x32_bf16 v[164:167], v[128:131], v[152:155], v[164:167]
	v_mfma_f32_16x16x32_bf16 v[108:111], v[120:123], v[160:163], v[108:111]
	v_mfma_f32_16x16x32_bf16 v[104:107], v[128:131], v[160:163], v[104:107]
	v_mfma_f32_16x16x32_bf16 v[92:95], v[120:123], v[176:179], v[92:95]
	v_mfma_f32_16x16x32_bf16 v[88:91], v[128:131], v[176:179], v[88:91]
	v_mfma_f32_16x16x32_bf16 v[76:79], v[120:123], v[184:187], v[76:79]
	v_mfma_f32_16x16x32_bf16 v[72:75], v[128:131], v[184:187], v[72:75]
	v_mfma_f32_16x16x32_bf16 v[168:171], v[124:127], v[156:159], v[168:171]
	v_mfma_f32_16x16x32_bf16 v[164:167], v[132:135], v[156:159], v[164:167]
	v_mfma_f32_16x16x32_bf16 v[108:111], v[124:127], v[172:175], v[108:111]
	v_mfma_f32_16x16x32_bf16 v[104:107], v[132:135], v[172:175], v[104:107]
	v_mfma_f32_16x16x32_bf16 v[92:95], v[124:127], v[180:183], v[92:95]
	v_mfma_f32_16x16x32_bf16 v[88:91], v[132:135], v[180:183], v[88:91]
	v_mfma_f32_16x16x32_bf16 v[76:79], v[124:127], v[208:211], v[76:79]
	v_mfma_f32_16x16x32_bf16 v[72:75], v[132:135], v[208:211], v[72:75]
	v_mfma_f32_16x16x32_bf16 v[116:119], v[136:139], v[152:155], v[116:119]
	v_mfma_f32_16x16x32_bf16 v[112:115], v[144:147], v[152:155], v[112:115]
	v_mfma_f32_16x16x32_bf16 v[100:103], v[136:139], v[160:163], v[100:103]
	v_mfma_f32_16x16x32_bf16 v[96:99], v[144:147], v[160:163], v[96:99]
	v_mfma_f32_16x16x32_bf16 v[84:87], v[136:139], v[176:179], v[84:87]
	v_mfma_f32_16x16x32_bf16 v[80:83], v[144:147], v[176:179], v[80:83]
	v_mfma_f32_16x16x32_bf16 v[68:71], v[136:139], v[184:187], v[68:71]
	v_mfma_f32_16x16x32_bf16 v[64:67], v[144:147], v[184:187], v[64:67]
	v_mfma_f32_16x16x32_bf16 v[116:119], v[140:143], v[156:159], v[116:119]
	v_mfma_f32_16x16x32_bf16 v[112:115], v[148:151], v[156:159], v[112:115]
	v_mfma_f32_16x16x32_bf16 v[100:103], v[140:143], v[172:175], v[100:103]
	v_mfma_f32_16x16x32_bf16 v[96:99], v[148:151], v[172:175], v[96:99]
	v_mfma_f32_16x16x32_bf16 v[84:87], v[140:143], v[180:183], v[84:87]
	v_mfma_f32_16x16x32_bf16 v[80:83], v[148:151], v[180:183], v[80:83]
	v_mfma_f32_16x16x32_bf16 v[68:71], v[140:143], v[208:211], v[68:71]
	v_mfma_f32_16x16x32_bf16 v[64:67], v[148:151], v[208:211], v[64:67]
	s_barrier
	s_setprio 0
	s_add_i32 s3, s3, s89
	s_add_u32 s100, vcc_lo, 0x80
	s_addc_u32 s101, vcc_hi, 0
	s_mov_b32 m0, s3
	ds_read_b128 v[152:155], v248 offset:49152
	ds_read_b128 v[156:159], v248 offset:50176
	ds_read_b128 v[160:163], v248 offset:51200
	ds_read_b128 v[172:175], v248 offset:52224
	ds_read_b128 v[176:179], v248 offset:53248
	ds_read_b128 v[180:183], v248 offset:54272
	ds_read_b128 v[184:187], v248 offset:55296
	ds_read_b128 v[208:211], v248 offset:56320
	global_load_lds_dwordx4 v188, s[100:101]
	s_add_i32 m0, s3, 0x2000
	s_add_i32 s3, s33, s89
	global_load_lds_dwordx4 v206, s[100:101]
	s_add_u32 s36, s100, s92
	s_addc_u32 s37, s101, 0
	s_mov_b32 m0, s3
	s_nop 0
	global_load_lds_dwordx4 v188, s[36:37]
	s_add_i32 m0, s3, 0x2000
	s_nop 0
	global_load_lds_dwordx4 v206, s[36:37]
	s_add_u32 s100, s46, 0x80
	s_addc_u32 s101, s47, 0
	s_mov_b32 m0, s76
	s_nop 0
	global_load_lds_dwordx4 v202, s[100:101]
	s_mov_b32 m0, s77
	s_nop 0
	global_load_lds_dwordx4 v204, s[100:101]
	s_waitcnt vmcnt(8)
	s_waitcnt lgkmcnt(0)
	s_setprio 1
	s_barrier
	v_mfma_f32_16x16x32_bf16 v[60:63], v[120:123], v[152:155], v[60:63]
	v_mfma_f32_16x16x32_bf16 v[56:59], v[128:131], v[152:155], v[56:59]
	v_mfma_f32_16x16x32_bf16 v[44:47], v[120:123], v[160:163], v[44:47]
	v_mfma_f32_16x16x32_bf16 v[40:43], v[128:131], v[160:163], v[40:43]
	v_mfma_f32_16x16x32_bf16 v[28:31], v[120:123], v[176:179], v[28:31]
	v_mfma_f32_16x16x32_bf16 v[24:27], v[128:131], v[176:179], v[24:27]
	v_mfma_f32_16x16x32_bf16 v[12:15], v[120:123], v[184:187], v[12:15]
	v_mfma_f32_16x16x32_bf16 v[8:11], v[128:131], v[184:187], v[8:11]
	v_mfma_f32_16x16x32_bf16 v[60:63], v[124:127], v[156:159], v[60:63]
	v_mfma_f32_16x16x32_bf16 v[56:59], v[132:135], v[156:159], v[56:59]
	v_mfma_f32_16x16x32_bf16 v[44:47], v[124:127], v[172:175], v[44:47]
	v_mfma_f32_16x16x32_bf16 v[40:43], v[132:135], v[172:175], v[40:43]
	v_mfma_f32_16x16x32_bf16 v[28:31], v[124:127], v[180:183], v[28:31]
	v_mfma_f32_16x16x32_bf16 v[24:27], v[132:135], v[180:183], v[24:27]
	v_mfma_f32_16x16x32_bf16 v[12:15], v[124:127], v[208:211], v[12:15]
	v_mfma_f32_16x16x32_bf16 v[8:11], v[132:135], v[208:211], v[8:11]
	v_mfma_f32_16x16x32_bf16 v[52:55], v[136:139], v[152:155], v[52:55]
	v_mfma_f32_16x16x32_bf16 v[48:51], v[144:147], v[152:155], v[48:51]
	v_mfma_f32_16x16x32_bf16 v[36:39], v[136:139], v[160:163], v[36:39]
	v_mfma_f32_16x16x32_bf16 v[32:35], v[144:147], v[160:163], v[32:35]
	v_mfma_f32_16x16x32_bf16 v[20:23], v[136:139], v[176:179], v[20:23]
	v_mfma_f32_16x16x32_bf16 v[16:19], v[144:147], v[176:179], v[16:19]
	v_mfma_f32_16x16x32_bf16 v[4:7], v[136:139], v[184:187], v[4:7]
	v_mfma_f32_16x16x32_bf16 v[0:3], v[144:147], v[184:187], v[0:3]
	v_mfma_f32_16x16x32_bf16 v[52:55], v[140:143], v[156:159], v[52:55]
	v_mfma_f32_16x16x32_bf16 v[48:51], v[148:151], v[156:159], v[48:51]
	v_mfma_f32_16x16x32_bf16 v[36:39], v[140:143], v[172:175], v[36:39]
	v_mfma_f32_16x16x32_bf16 v[32:35], v[148:151], v[172:175], v[32:35]
	v_mfma_f32_16x16x32_bf16 v[20:23], v[140:143], v[180:183], v[20:23]
	v_mfma_f32_16x16x32_bf16 v[16:19], v[148:151], v[180:183], v[16:19]
	v_mfma_f32_16x16x32_bf16 v[4:7], v[140:143], v[208:211], v[4:7]
	v_mfma_f32_16x16x32_bf16 v[0:3], v[148:151], v[208:211], v[0:3]
	s_barrier
	s_setprio 0
	s_add_i32 s86, s86, 2
	s_cmp_ge_u32 s86, s98
	s_mov_b64 s[36:37], s[38:39]
	s_cbranch_scc1 .Lpeel_exit_resid
.LBB0_490:
	s_add_u32 s38, s36, 0x100
	s_addc_u32 s39, s37, 0
	s_cmp_ge_u32 s38, s24
	s_cselect_b32 s47, s24, 0
	s_cselect_b32 s46, 0, 0
	s_sub_u32 s38, s38, s47
	s_subb_u32 s39, s39, s46
	s_sub_u32 s47, s36, s47
	s_subb_u32 s46, s37, s46
	s_add_u32 vcc_lo, s34, s47
	s_addc_u32 vcc_hi, s35, s46
	s_add_u32 vcc_lo, vcc_lo, 0x100
	s_addc_u32 vcc_hi, vcc_hi, 0
	s_add_u32 s47, s30, s47
	s_addc_u32 s46, s31, s46
	s_add_u32 s69, s47, 0x100
	s_addc_u32 s3, s46, 0
	s_add_i32 s33, 0, 0x10000
	s_cmp_eq_u32 s99, s86
	s_cselect_b32 s47, s11, vcc_hi
	s_cselect_b32 s46, s10, vcc_lo
	s_cselect_b32 vcc_hi, s29, s3
	s_cselect_b32 vcc_lo, s28, s69
	s_add_i32 s3, 0, 0x14000
	ds_read_b128 v[120:123], v212
	ds_read_b128 v[124:127], v212 offset:1024
	ds_read_b128 v[128:131], v212 offset:2048
	ds_read_b128 v[132:135], v212 offset:3072
	ds_read_b128 v[136:139], v212 offset:16384
	ds_read_b128 v[140:143], v212 offset:17408
	ds_read_b128 v[144:147], v212 offset:18432
	ds_read_b128 v[148:151], v212 offset:19456
	s_add_u32 s36, s0, s36
	s_addc_u32 s37, s43, s37
	s_add_u32 s100, s36, 0x80
	s_addc_u32 s101, s37, 0
	s_add_i32 m0, s94, 0xc000
	ds_read_b128 v[152:155], v248
	ds_read_b128 v[156:159], v248 offset:1024
	ds_read_b128 v[160:163], v248 offset:2048
	ds_read_b128 v[172:175], v248 offset:3072
	ds_read_b128 v[176:179], v248 offset:4096
	ds_read_b128 v[180:183], v248 offset:5120
	ds_read_b128 v[184:187], v248 offset:6144
	ds_read_b128 v[208:211], v248 offset:7168
	global_load_lds_dwordx4 v202, s[100:101]
	s_add_i32 m0, s94, 0xe000
	s_nop 0
	global_load_lds_dwordx4 v204, s[100:101]
	s_waitcnt vmcnt(8)
	s_waitcnt lgkmcnt(0)
	s_setprio 1
	s_barrier
	v_mfma_f32_16x16x32_bf16 v[168:171], v[120:123], v[152:155], v[168:171]
	v_mfma_f32_16x16x32_bf16 v[164:167], v[128:131], v[152:155], v[164:167]
	v_mfma_f32_16x16x32_bf16 v[108:111], v[120:123], v[160:163], v[108:111]
	v_mfma_f32_16x16x32_bf16 v[104:107], v[128:131], v[160:163], v[104:107]
	v_mfma_f32_16x16x32_bf16 v[92:95], v[120:123], v[176:179], v[92:95]
	v_mfma_f32_16x16x32_bf16 v[88:91], v[128:131], v[176:179], v[88:91]
	v_mfma_f32_16x16x32_bf16 v[76:79], v[120:123], v[184:187], v[76:79]
	v_mfma_f32_16x16x32_bf16 v[72:75], v[128:131], v[184:187], v[72:75]
	v_mfma_f32_16x16x32_bf16 v[168:171], v[124:127], v[156:159], v[168:171]
	v_mfma_f32_16x16x32_bf16 v[164:167], v[132:135], v[156:159], v[164:167]
	v_mfma_f32_16x16x32_bf16 v[108:111], v[124:127], v[172:175], v[108:111]
	v_mfma_f32_16x16x32_bf16 v[104:107], v[132:135], v[172:175], v[104:107]
	v_mfma_f32_16x16x32_bf16 v[92:95], v[124:127], v[180:183], v[92:95]
	v_mfma_f32_16x16x32_bf16 v[88:91], v[132:135], v[180:183], v[88:91]
	v_mfma_f32_16x16x32_bf16 v[76:79], v[124:127], v[208:211], v[76:79]
	v_mfma_f32_16x16x32_bf16 v[72:75], v[132:135], v[208:211], v[72:75]
	v_mfma_f32_16x16x32_bf16 v[116:119], v[136:139], v[152:155], v[116:119]
	v_mfma_f32_16x16x32_bf16 v[112:115], v[144:147], v[152:155], v[112:115]
	v_mfma_f32_16x16x32_bf16 v[100:103], v[136:139], v[160:163], v[100:103]
	v_mfma_f32_16x16x32_bf16 v[96:99], v[144:147], v[160:163], v[96:99]
	v_mfma_f32_16x16x32_bf16 v[84:87], v[136:139], v[176:179], v[84:87]
	v_mfma_f32_16x16x32_bf16 v[80:83], v[144:147], v[176:179], v[80:83]
	v_mfma_f32_16x16x32_bf16 v[68:71], v[136:139], v[184:187], v[68:71]
	v_mfma_f32_16x16x32_bf16 v[64:67], v[144:147], v[184:187], v[64:67]
	v_mfma_f32_16x16x32_bf16 v[116:119], v[140:143], v[156:159], v[116:119]
	v_mfma_f32_16x16x32_bf16 v[112:115], v[148:151], v[156:159], v[112:115]
	v_mfma_f32_16x16x32_bf16 v[100:103], v[140:143], v[172:175], v[100:103]
	v_mfma_f32_16x16x32_bf16 v[96:99], v[148:151], v[172:175], v[96:99]
	v_mfma_f32_16x16x32_bf16 v[84:87], v[140:143], v[180:183], v[84:87]
	v_mfma_f32_16x16x32_bf16 v[80:83], v[148:151], v[180:183], v[80:83]
	v_mfma_f32_16x16x32_bf16 v[68:71], v[140:143], v[208:211], v[68:71]
	v_mfma_f32_16x16x32_bf16 v[64:67], v[148:151], v[208:211], v[64:67]
	s_barrier
	s_setprio 0
	s_add_i32 s33, s33, s89
	s_mov_b64 s[100:101], vcc
	s_mov_b32 m0, s33
	ds_read_b128 v[152:155], v248 offset:16384
	ds_read_b128 v[156:159], v248 offset:17408
	ds_read_b128 v[160:163], v248 offset:18432
	ds_read_b128 v[172:175], v248 offset:19456
	ds_read_b128 v[176:179], v248 offset:20480
	ds_read_b128 v[180:183], v248 offset:21504
	ds_read_b128 v[184:187], v248 offset:22528
	ds_read_b128 v[208:211], v248 offset:23552
	global_load_lds_dwordx4 v188, s[100:101]
	s_add_i32 m0, s33, 0x2000
	s_add_u32 s36, vcc_lo, s92
	s_addc_u32 s37, vcc_hi, 0
	s_add_i32 s3, s3, s89
	global_load_lds_dwordx4 v206, s[100:101]
	s_mov_b32 m0, s3
	s_nop 0
	global_load_lds_dwordx4 v188, s[36:37]
	s_add_i32 m0, s3, 0x2000
	s_nop 0
	global_load_lds_dwordx4 v206, s[36:37]
	s_mov_b32 m0, s94
	s_nop 0
	global_load_lds_dwordx4 v202, s[46:47]
	s_mov_b32 m0, s95
	s_nop 0
	global_load_lds_dwordx4 v204, s[46:47]
	s_waitcnt vmcnt(8)
	s_waitcnt lgkmcnt(0)
	s_setprio 1
	s_barrier
	v_mfma_f32_16x16x32_bf16 v[60:63], v[120:123], v[152:155], v[60:63]
	v_mfma_f32_16x16x32_bf16 v[56:59], v[128:131], v[152:155], v[56:59]
	v_mfma_f32_16x16x32_bf16 v[44:47], v[120:123], v[160:163], v[44:47]
	v_mfma_f32_16x16x32_bf16 v[40:43], v[128:131], v[160:163], v[40:43]
	v_mfma_f32_16x16x32_bf16 v[28:31], v[120:123], v[176:179], v[28:31]
	v_mfma_f32_16x16x32_bf16 v[24:27], v[128:131], v[176:179], v[24:27]
	v_mfma_f32_16x16x32_bf16 v[12:15], v[120:123], v[184:187], v[12:15]
	v_mfma_f32_16x16x32_bf16 v[8:11], v[128:131], v[184:187], v[8:11]
	v_mfma_f32_16x16x32_bf16 v[60:63], v[124:127], v[156:159], v[60:63]
	v_mfma_f32_16x16x32_bf16 v[56:59], v[132:135], v[156:159], v[56:59]
	v_mfma_f32_16x16x32_bf16 v[44:47], v[124:127], v[172:175], v[44:47]
	v_mfma_f32_16x16x32_bf16 v[40:43], v[132:135], v[172:175], v[40:43]
	v_mfma_f32_16x16x32_bf16 v[28:31], v[124:127], v[180:183], v[28:31]
	v_mfma_f32_16x16x32_bf16 v[24:27], v[132:135], v[180:183], v[24:27]
	v_mfma_f32_16x16x32_bf16 v[12:15], v[124:127], v[208:211], v[12:15]
	v_mfma_f32_16x16x32_bf16 v[8:11], v[132:135], v[208:211], v[8:11]
	v_mfma_f32_16x16x32_bf16 v[52:55], v[136:139], v[152:155], v[52:55]
	v_mfma_f32_16x16x32_bf16 v[48:51], v[144:147], v[152:155], v[48:51]
	v_mfma_f32_16x16x32_bf16 v[36:39], v[136:139], v[160:163], v[36:39]
	v_mfma_f32_16x16x32_bf16 v[32:35], v[144:147], v[160:163], v[32:35]
	v_mfma_f32_16x16x32_bf16 v[20:23], v[136:139], v[176:179], v[20:23]
	v_mfma_f32_16x16x32_bf16 v[16:19], v[144:147], v[176:179], v[16:19]
	v_mfma_f32_16x16x32_bf16 v[4:7], v[136:139], v[184:187], v[4:7]
	v_mfma_f32_16x16x32_bf16 v[0:3], v[144:147], v[184:187], v[0:3]
	v_mfma_f32_16x16x32_bf16 v[52:55], v[140:143], v[156:159], v[52:55]
	v_mfma_f32_16x16x32_bf16 v[48:51], v[148:151], v[156:159], v[48:51]
	v_mfma_f32_16x16x32_bf16 v[36:39], v[140:143], v[172:175], v[36:39]
	v_mfma_f32_16x16x32_bf16 v[32:35], v[148:151], v[172:175], v[32:35]
	v_mfma_f32_16x16x32_bf16 v[20:23], v[140:143], v[180:183], v[20:23]
	v_mfma_f32_16x16x32_bf16 v[16:19], v[148:151], v[180:183], v[16:19]
	v_mfma_f32_16x16x32_bf16 v[4:7], v[140:143], v[208:211], v[4:7]
	v_mfma_f32_16x16x32_bf16 v[0:3], v[148:151], v[208:211], v[0:3]
	s_barrier
	s_setprio 0
	s_add_i32 s3, 0, 0x18000
	s_add_i32 s33, 0, 0x1c000
	ds_read_b128 v[120:123], v212 offset:32768
	ds_read_b128 v[124:127], v212 offset:33792
	ds_read_b128 v[128:131], v212 offset:34816
	ds_read_b128 v[132:135], v212 offset:35840
	ds_read_b128 v[136:139], v212 offset:49152
	ds_read_b128 v[140:143], v212 offset:50176
	ds_read_b128 v[144:147], v212 offset:51200
	ds_read_b128 v[148:151], v212 offset:52224
	s_add_u32 s36, s46, s92
	s_addc_u32 s37, s47, 0
	s_mov_b32 m0, s96
	ds_read_b128 v[152:155], v248 offset:32768
	ds_read_b128 v[156:159], v248 offset:33792
	ds_read_b128 v[160:163], v248 offset:34816
	ds_read_b128 v[172:175], v248 offset:35840
	ds_read_b128 v[176:179], v248 offset:36864
	ds_read_b128 v[180:183], v248 offset:37888
	ds_read_b128 v[184:187], v248 offset:38912
	ds_read_b128 v[208:211], v248 offset:39936
	global_load_lds_dwordx4 v202, s[36:37]
	s_mov_b32 m0, s97
	s_nop 0
	global_load_lds_dwordx4 v204, s[36:37]
	s_waitcnt vmcnt(8)
	s_waitcnt lgkmcnt(0)
	s_setprio 1
	s_barrier
	v_mfma_f32_16x16x32_bf16 v[168:171], v[120:123], v[152:155], v[168:171]
	v_mfma_f32_16x16x32_bf16 v[164:167], v[128:131], v[152:155], v[164:167]
	v_mfma_f32_16x16x32_bf16 v[108:111], v[120:123], v[160:163], v[108:111]
	v_mfma_f32_16x16x32_bf16 v[104:107], v[128:131], v[160:163], v[104:107]
	v_mfma_f32_16x16x32_bf16 v[92:95], v[120:123], v[176:179], v[92:95]
	v_mfma_f32_16x16x32_bf16 v[88:91], v[128:131], v[176:179], v[88:91]
	v_mfma_f32_16x16x32_bf16 v[76:79], v[120:123], v[184:187], v[76:79]
	v_mfma_f32_16x16x32_bf16 v[72:75], v[128:131], v[184:187], v[72:75]
	v_mfma_f32_16x16x32_bf16 v[168:171], v[124:127], v[156:159], v[168:171]
	v_mfma_f32_16x16x32_bf16 v[164:167], v[132:135], v[156:159], v[164:167]
	v_mfma_f32_16x16x32_bf16 v[108:111], v[124:127], v[172:175], v[108:111]
	v_mfma_f32_16x16x32_bf16 v[104:107], v[132:135], v[172:175], v[104:107]
	v_mfma_f32_16x16x32_bf16 v[92:95], v[124:127], v[180:183], v[92:95]
	v_mfma_f32_16x16x32_bf16 v[88:91], v[132:135], v[180:183], v[88:91]
	v_mfma_f32_16x16x32_bf16 v[76:79], v[124:127], v[208:211], v[76:79]
	v_mfma_f32_16x16x32_bf16 v[72:75], v[132:135], v[208:211], v[72:75]
	v_mfma_f32_16x16x32_bf16 v[116:119], v[136:139], v[152:155], v[116:119]
	v_mfma_f32_16x16x32_bf16 v[112:115], v[144:147], v[152:155], v[112:115]
	v_mfma_f32_16x16x32_bf16 v[100:103], v[136:139], v[160:163], v[100:103]
	v_mfma_f32_16x16x32_bf16 v[96:99], v[144:147], v[160:163], v[96:99]
	v_mfma_f32_16x16x32_bf16 v[84:87], v[136:139], v[176:179], v[84:87]
	v_mfma_f32_16x16x32_bf16 v[80:83], v[144:147], v[176:179], v[80:83]
	v_mfma_f32_16x16x32_bf16 v[68:71], v[136:139], v[184:187], v[68:71]
	v_mfma_f32_16x16x32_bf16 v[64:67], v[144:147], v[184:187], v[64:67]
	v_mfma_f32_16x16x32_bf16 v[116:119], v[140:143], v[156:159], v[116:119]
	v_mfma_f32_16x16x32_bf16 v[112:115], v[148:151], v[156:159], v[112:115]
	v_mfma_f32_16x16x32_bf16 v[100:103], v[140:143], v[172:175], v[100:103]
	v_mfma_f32_16x16x32_bf16 v[96:99], v[148:151], v[172:175], v[96:99]
	v_mfma_f32_16x16x32_bf16 v[84:87], v[140:143], v[180:183], v[84:87]
	v_mfma_f32_16x16x32_bf16 v[80:83], v[148:151], v[180:183], v[80:83]
	v_mfma_f32_16x16x32_bf16 v[68:71], v[140:143], v[208:211], v[68:71]
	v_mfma_f32_16x16x32_bf16 v[64:67], v[148:151], v[208:211], v[64:67]
	s_barrier
	s_setprio 0
	s_add_i32 s3, s3, s89
	s_add_u32 s100, vcc_lo, 0x80
	s_addc_u32 s101, vcc_hi, 0
	s_mov_b32 m0, s3
	ds_read_b128 v[152:155], v248 offset:49152
	ds_read_b128 v[156:159], v248 offset:50176
	ds_read_b128 v[160:163], v248 offset:51200
	ds_read_b128 v[172:175], v248 offset:52224
	ds_read_b128 v[176:179], v248 offset:53248
	ds_read_b128 v[180:183], v248 offset:54272
	ds_read_b128 v[184:187], v248 offset:55296
	ds_read_b128 v[208:211], v248 offset:56320
	global_load_lds_dwordx4 v188, s[100:101]
	s_add_i32 m0, s3, 0x2000
	s_add_i32 s3, s33, s89
	global_load_lds_dwordx4 v206, s[100:101]
	s_add_u32 s36, s100, s92
	s_addc_u32 s37, s101, 0
	s_mov_b32 m0, s3
	s_nop 0
	global_load_lds_dwordx4 v188, s[36:37]
	s_add_i32 m0, s3, 0x2000
	s_nop 0
	global_load_lds_dwordx4 v206, s[36:37]
	s_add_u32 s100, s46, 0x80
	s_addc_u32 s101, s47, 0
	s_mov_b32 m0, s76
	s_nop 0
	global_load_lds_dwordx4 v202, s[100:101]
	s_mov_b32 m0, s77
	s_nop 0
	global_load_lds_dwordx4 v204, s[100:101]
	s_waitcnt vmcnt(8)
	s_waitcnt lgkmcnt(0)
	s_setprio 1
	s_barrier
	v_mfma_f32_16x16x32_bf16 v[60:63], v[120:123], v[152:155], v[60:63]
	v_mfma_f32_16x16x32_bf16 v[56:59], v[128:131], v[152:155], v[56:59]
	v_mfma_f32_16x16x32_bf16 v[44:47], v[120:123], v[160:163], v[44:47]
	v_mfma_f32_16x16x32_bf16 v[40:43], v[128:131], v[160:163], v[40:43]
	v_mfma_f32_16x16x32_bf16 v[28:31], v[120:123], v[176:179], v[28:31]
	v_mfma_f32_16x16x32_bf16 v[24:27], v[128:131], v[176:179], v[24:27]
	v_mfma_f32_16x16x32_bf16 v[12:15], v[120:123], v[184:187], v[12:15]
	v_mfma_f32_16x16x32_bf16 v[8:11], v[128:131], v[184:187], v[8:11]
	v_mfma_f32_16x16x32_bf16 v[60:63], v[124:127], v[156:159], v[60:63]
	v_mfma_f32_16x16x32_bf16 v[56:59], v[132:135], v[156:159], v[56:59]
	v_mfma_f32_16x16x32_bf16 v[44:47], v[124:127], v[172:175], v[44:47]
	v_mfma_f32_16x16x32_bf16 v[40:43], v[132:135], v[172:175], v[40:43]
	v_mfma_f32_16x16x32_bf16 v[28:31], v[124:127], v[180:183], v[28:31]
	v_mfma_f32_16x16x32_bf16 v[24:27], v[132:135], v[180:183], v[24:27]
	v_mfma_f32_16x16x32_bf16 v[12:15], v[124:127], v[208:211], v[12:15]
	v_mfma_f32_16x16x32_bf16 v[8:11], v[132:135], v[208:211], v[8:11]
	v_mfma_f32_16x16x32_bf16 v[52:55], v[136:139], v[152:155], v[52:55]
	v_mfma_f32_16x16x32_bf16 v[48:51], v[144:147], v[152:155], v[48:51]
	v_mfma_f32_16x16x32_bf16 v[36:39], v[136:139], v[160:163], v[36:39]
	v_mfma_f32_16x16x32_bf16 v[32:35], v[144:147], v[160:163], v[32:35]
	v_mfma_f32_16x16x32_bf16 v[20:23], v[136:139], v[176:179], v[20:23]
	v_mfma_f32_16x16x32_bf16 v[16:19], v[144:147], v[176:179], v[16:19]
	v_mfma_f32_16x16x32_bf16 v[4:7], v[136:139], v[184:187], v[4:7]
	v_mfma_f32_16x16x32_bf16 v[0:3], v[144:147], v[184:187], v[0:3]
	v_mfma_f32_16x16x32_bf16 v[52:55], v[140:143], v[156:159], v[52:55]
	v_mfma_f32_16x16x32_bf16 v[48:51], v[148:151], v[156:159], v[48:51]
	v_mfma_f32_16x16x32_bf16 v[36:39], v[140:143], v[172:175], v[36:39]
	v_mfma_f32_16x16x32_bf16 v[32:35], v[148:151], v[172:175], v[32:35]
	v_mfma_f32_16x16x32_bf16 v[20:23], v[140:143], v[180:183], v[20:23]
	v_mfma_f32_16x16x32_bf16 v[16:19], v[148:151], v[180:183], v[16:19]
	v_mfma_f32_16x16x32_bf16 v[4:7], v[140:143], v[208:211], v[4:7]
	v_mfma_f32_16x16x32_bf16 v[0:3], v[148:151], v[208:211], v[0:3]
	s_barrier
	s_setprio 0
	s_add_i32 s86, s86, 2
	s_cmp_ge_u32 s86, s98
	s_mov_b64 s[36:37], s[38:39]
	s_cbranch_scc0 .LBB0_490

.LBB0_527:
	s_ashr_i32 s19, s18, 31
	s_lshl_b64 s[20:21], s[18:19], 19
	s_add_u32 s20, s50, s20
	s_addc_u32 s21, s51, s21
	s_and_b64 s[22:23], s[4:5], exec
	s_cselect_b32 s19, s21, s29
	s_cselect_b32 s25, s20, s28
	s_ashr_i32 s17, s16, 31
	s_lshl_b64 s[22:23], s[16:17], 19
	s_add_u32 s22, s46, s22
	s_addc_u32 s23, s47, s23
	s_and_b64 s[30:31], s[4:5], exec
	s_cselect_b32 s0, s23, s27
	s_cselect_b32 s17, s22, s26
	s_mov_b64 s[30:31], 0
	s_mov_b32 s43, -2
	v_add_u32_e32 v186, 0x10000, v141
	s_add_u32 s34, s30, 0x100
	s_addc_u32 s35, s31, 0
	s_add_u32 s38, s30, 0xfffff900
	s_addc_u32 s39, s31, -1
	s_cmp_gt_u32 s34, 0x7ff
	s_cselect_b32 s34, s38, s34
	s_cselect_b32 s35, s39, s35
	s_add_u32 s36, s28, s34
	s_addc_u32 s37, s29, s35
	s_add_u32 s76, s26, s34
	s_addc_u32 s77, s27, s35
	s_add_i32 s86, 0, 0x10000
	s_cmp_eq_u32 s43, 12
	s_cselect_b32 s39, s19, s37
	s_cselect_b32 s38, s25, s36
	s_cselect_b32 s37, s0, s77
	s_cselect_b32 s36, s17, s76
	s_add_i32 s76, 0, 0x14000
	ds_read_b128 v[96:99], v186
	ds_read_b128 v[150:153], v186 offset:1024
	ds_read_b128 v[154:157], v186 offset:2048
	ds_read_b128 v[158:161], v186 offset:3072
	ds_read_b128 v[162:165], v186 offset:16384
	ds_read_b128 v[166:169], v186 offset:17408
	ds_read_b128 v[170:173], v186 offset:18432
	ds_read_b128 v[174:177], v186 offset:19456
	s_add_u32 s30, s28, s30
	s_addc_u32 s31, s29, s31
	s_add_u32 s30, s30, 0x40080
	s_addc_u32 s31, s31, 0
	s_add_i32 m0, s60, 0xc000
	ds_read_b128 v[178:181], v149
	ds_read_b128 v[182:185], v149 offset:1024
	ds_read_b128 v[202:205], v149 offset:2048
	ds_read_b128 v[206:209], v149 offset:3072
	ds_read_b128 v[210:213], v149 offset:4096
	ds_read_b128 v[214:217], v149 offset:5120
	ds_read_b128 v[218:221], v149 offset:6144
	ds_read_b128 v[222:225], v149 offset:7168
	global_load_lds_dwordx4 v136, s[30:31]
	s_add_i32 m0, s60, 0xe000
	s_nop 0
	global_load_lds_dwordx4 v134, s[30:31]
	s_waitcnt vmcnt(8)
	s_waitcnt lgkmcnt(0)
	s_setprio 1
	s_barrier
	v_mfma_f32_16x16x32_bf16 v[128:131], v[96:99], v[178:181], 0
	v_mfma_f32_16x16x32_bf16 v[120:123], v[154:157], v[178:181], 0
	v_mfma_f32_16x16x32_bf16 v[112:115], v[96:99], v[202:205], 0
	v_mfma_f32_16x16x32_bf16 v[104:107], v[154:157], v[202:205], 0
	v_mfma_f32_16x16x32_bf16 v[92:95], v[96:99], v[210:213], 0
	v_mfma_f32_16x16x32_bf16 v[84:87], v[154:157], v[210:213], 0
	v_mfma_f32_16x16x32_bf16 v[76:79], v[96:99], v[218:221], 0
	v_mfma_f32_16x16x32_bf16 v[68:71], v[154:157], v[218:221], 0
	v_mfma_f32_16x16x32_bf16 v[128:131], v[150:153], v[182:185], v[128:131]
	v_mfma_f32_16x16x32_bf16 v[120:123], v[158:161], v[182:185], v[120:123]
	v_mfma_f32_16x16x32_bf16 v[112:115], v[150:153], v[206:209], v[112:115]
	v_mfma_f32_16x16x32_bf16 v[104:107], v[158:161], v[206:209], v[104:107]
	v_mfma_f32_16x16x32_bf16 v[92:95], v[150:153], v[214:217], v[92:95]
	v_mfma_f32_16x16x32_bf16 v[84:87], v[158:161], v[214:217], v[84:87]
	v_mfma_f32_16x16x32_bf16 v[76:79], v[150:153], v[222:225], v[76:79]
	v_mfma_f32_16x16x32_bf16 v[68:71], v[158:161], v[222:225], v[68:71]
	v_mfma_f32_16x16x32_bf16 v[124:127], v[162:165], v[178:181], 0
	v_mfma_f32_16x16x32_bf16 v[116:119], v[170:173], v[178:181], 0
	v_mfma_f32_16x16x32_bf16 v[108:111], v[162:165], v[202:205], 0
	v_mfma_f32_16x16x32_bf16 v[100:103], v[170:173], v[202:205], 0
	v_mfma_f32_16x16x32_bf16 v[88:91], v[162:165], v[210:213], 0
	v_mfma_f32_16x16x32_bf16 v[80:83], v[170:173], v[210:213], 0
	v_mfma_f32_16x16x32_bf16 v[72:75], v[162:165], v[218:221], 0
	v_mfma_f32_16x16x32_bf16 v[64:67], v[170:173], v[218:221], 0
	v_mfma_f32_16x16x32_bf16 v[124:127], v[166:169], v[182:185], v[124:127]
	v_mfma_f32_16x16x32_bf16 v[116:119], v[174:177], v[182:185], v[116:119]
	v_mfma_f32_16x16x32_bf16 v[108:111], v[166:169], v[206:209], v[108:111]
	v_mfma_f32_16x16x32_bf16 v[100:103], v[174:177], v[206:209], v[100:103]
	v_mfma_f32_16x16x32_bf16 v[88:91], v[166:169], v[214:217], v[88:91]
	v_mfma_f32_16x16x32_bf16 v[80:83], v[174:177], v[214:217], v[80:83]
	v_mfma_f32_16x16x32_bf16 v[72:75], v[166:169], v[222:225], v[72:75]
	v_mfma_f32_16x16x32_bf16 v[64:67], v[174:177], v[222:225], v[64:67]
	s_barrier
	s_setprio 0
	s_add_i32 s30, s86, s56
	s_mov_b32 m0, s30
	ds_read_b128 v[178:181], v149 offset:16384
	ds_read_b128 v[182:185], v149 offset:17408
	ds_read_b128 v[202:205], v149 offset:18432
	ds_read_b128 v[206:209], v149 offset:19456
	ds_read_b128 v[210:213], v149 offset:20480
	ds_read_b128 v[214:217], v149 offset:21504
	ds_read_b128 v[218:221], v149 offset:22528
	ds_read_b128 v[222:225], v149 offset:23552
	global_load_lds_dwordx4 v188, s[36:37]
	s_add_i32 m0, s30, 0x2000
	s_add_u32 s30, s36, 0x40000
	s_addc_u32 s31, s37, 0
	s_add_i32 s76, s76, s56
	global_load_lds_dwordx4 v132, s[36:37]
	s_mov_b32 m0, s76
	s_nop 0
	global_load_lds_dwordx4 v188, s[30:31]
	s_add_i32 m0, s76, 0x2000
	s_nop 0
	global_load_lds_dwordx4 v132, s[30:31]
	s_mov_b32 m0, s60
	s_nop 0
	global_load_lds_dwordx4 v136, s[38:39]
	s_mov_b32 m0, s71
	s_nop 0
	global_load_lds_dwordx4 v134, s[38:39]
	s_waitcnt vmcnt(8)
	s_waitcnt lgkmcnt(0)
	s_setprio 1
	s_barrier
	v_mfma_f32_16x16x32_bf16 v[60:63], v[96:99], v[178:181], 0
	v_mfma_f32_16x16x32_bf16 v[52:55], v[154:157], v[178:181], 0
	v_mfma_f32_16x16x32_bf16 v[44:47], v[96:99], v[202:205], 0
	v_mfma_f32_16x16x32_bf16 v[36:39], v[154:157], v[202:205], 0
	v_mfma_f32_16x16x32_bf16 v[28:31], v[96:99], v[210:213], 0
	v_mfma_f32_16x16x32_bf16 v[20:23], v[154:157], v[210:213], 0
	v_mfma_f32_16x16x32_bf16 v[12:15], v[96:99], v[218:221], 0
	v_mfma_f32_16x16x32_bf16 v[4:7], v[154:157], v[218:221], 0
	v_mfma_f32_16x16x32_bf16 v[60:63], v[150:153], v[182:185], v[60:63]
	v_mfma_f32_16x16x32_bf16 v[52:55], v[158:161], v[182:185], v[52:55]
	v_mfma_f32_16x16x32_bf16 v[44:47], v[150:153], v[206:209], v[44:47]
	v_mfma_f32_16x16x32_bf16 v[36:39], v[158:161], v[206:209], v[36:39]
	v_mfma_f32_16x16x32_bf16 v[28:31], v[150:153], v[214:217], v[28:31]
	v_mfma_f32_16x16x32_bf16 v[20:23], v[158:161], v[214:217], v[20:23]
	v_mfma_f32_16x16x32_bf16 v[12:15], v[150:153], v[222:225], v[12:15]
	v_mfma_f32_16x16x32_bf16 v[4:7], v[158:161], v[222:225], v[4:7]
	v_mfma_f32_16x16x32_bf16 v[56:59], v[162:165], v[178:181], 0
	v_mfma_f32_16x16x32_bf16 v[48:51], v[170:173], v[178:181], 0
	v_mfma_f32_16x16x32_bf16 v[40:43], v[162:165], v[202:205], 0
	v_mfma_f32_16x16x32_bf16 v[32:35], v[170:173], v[202:205], 0
	v_mfma_f32_16x16x32_bf16 v[24:27], v[162:165], v[210:213], 0
	v_mfma_f32_16x16x32_bf16 v[16:19], v[170:173], v[210:213], 0
	v_mfma_f32_16x16x32_bf16 v[8:11], v[162:165], v[218:221], 0
	v_mfma_f32_16x16x32_bf16 v[0:3], v[170:173], v[218:221], 0
	v_mfma_f32_16x16x32_bf16 v[56:59], v[166:169], v[182:185], v[56:59]
	v_mfma_f32_16x16x32_bf16 v[48:51], v[174:177], v[182:185], v[48:51]
	v_mfma_f32_16x16x32_bf16 v[40:43], v[166:169], v[206:209], v[40:43]
	v_mfma_f32_16x16x32_bf16 v[32:35], v[174:177], v[206:209], v[32:35]
	v_mfma_f32_16x16x32_bf16 v[24:27], v[166:169], v[214:217], v[24:27]
	v_mfma_f32_16x16x32_bf16 v[16:19], v[174:177], v[214:217], v[16:19]
	v_mfma_f32_16x16x32_bf16 v[8:11], v[166:169], v[222:225], v[8:11]
	v_mfma_f32_16x16x32_bf16 v[0:3], v[174:177], v[222:225], v[0:3]
	s_barrier
	s_setprio 0
	s_add_i32 s76, 0, 0x18000
	s_add_i32 s77, 0, 0x1c000
	ds_read_b128 v[96:99], v186 offset:32768
	ds_read_b128 v[150:153], v186 offset:33792
	ds_read_b128 v[154:157], v186 offset:34816
	ds_read_b128 v[158:161], v186 offset:35840
	ds_read_b128 v[162:165], v186 offset:49152
	ds_read_b128 v[166:169], v186 offset:50176
	ds_read_b128 v[170:173], v186 offset:51200
	ds_read_b128 v[174:177], v186 offset:52224
	s_add_u32 s30, s38, 0x40000
	s_addc_u32 s31, s39, 0
	s_mov_b32 m0, s87
	ds_read_b128 v[178:181], v149 offset:32768
	ds_read_b128 v[182:185], v149 offset:33792
	ds_read_b128 v[202:205], v149 offset:34816
	ds_read_b128 v[206:209], v149 offset:35840
	ds_read_b128 v[210:213], v149 offset:36864
	ds_read_b128 v[214:217], v149 offset:37888
	ds_read_b128 v[218:221], v149 offset:38912
	ds_read_b128 v[222:225], v149 offset:39936
	global_load_lds_dwordx4 v136, s[30:31]
	s_mov_b32 m0, s89
	s_nop 0
	global_load_lds_dwordx4 v134, s[30:31]
	s_waitcnt vmcnt(8)
	s_waitcnt lgkmcnt(0)
	s_setprio 1
	s_barrier
	v_mfma_f32_16x16x32_bf16 v[128:131], v[96:99], v[178:181], v[128:131]
	v_mfma_f32_16x16x32_bf16 v[120:123], v[154:157], v[178:181], v[120:123]
	v_mfma_f32_16x16x32_bf16 v[112:115], v[96:99], v[202:205], v[112:115]
	v_mfma_f32_16x16x32_bf16 v[104:107], v[154:157], v[202:205], v[104:107]
	v_mfma_f32_16x16x32_bf16 v[92:95], v[96:99], v[210:213], v[92:95]
	v_mfma_f32_16x16x32_bf16 v[84:87], v[154:157], v[210:213], v[84:87]
	v_mfma_f32_16x16x32_bf16 v[76:79], v[96:99], v[218:221], v[76:79]
	v_mfma_f32_16x16x32_bf16 v[68:71], v[154:157], v[218:221], v[68:71]
	v_mfma_f32_16x16x32_bf16 v[128:131], v[150:153], v[182:185], v[128:131]
	v_mfma_f32_16x16x32_bf16 v[120:123], v[158:161], v[182:185], v[120:123]
	v_mfma_f32_16x16x32_bf16 v[112:115], v[150:153], v[206:209], v[112:115]
	v_mfma_f32_16x16x32_bf16 v[104:107], v[158:161], v[206:209], v[104:107]
	v_mfma_f32_16x16x32_bf16 v[92:95], v[150:153], v[214:217], v[92:95]
	v_mfma_f32_16x16x32_bf16 v[84:87], v[158:161], v[214:217], v[84:87]
	v_mfma_f32_16x16x32_bf16 v[76:79], v[150:153], v[222:225], v[76:79]
	v_mfma_f32_16x16x32_bf16 v[68:71], v[158:161], v[222:225], v[68:71]
	v_mfma_f32_16x16x32_bf16 v[124:127], v[162:165], v[178:181], v[124:127]
	v_mfma_f32_16x16x32_bf16 v[116:119], v[170:173], v[178:181], v[116:119]
	v_mfma_f32_16x16x32_bf16 v[108:111], v[162:165], v[202:205], v[108:111]
	v_mfma_f32_16x16x32_bf16 v[100:103], v[170:173], v[202:205], v[100:103]
	v_mfma_f32_16x16x32_bf16 v[88:91], v[162:165], v[210:213], v[88:91]
	v_mfma_f32_16x16x32_bf16 v[80:83], v[170:173], v[210:213], v[80:83]
	v_mfma_f32_16x16x32_bf16 v[72:75], v[162:165], v[218:221], v[72:75]
	v_mfma_f32_16x16x32_bf16 v[64:67], v[170:173], v[218:221], v[64:67]
	v_mfma_f32_16x16x32_bf16 v[124:127], v[166:169], v[182:185], v[124:127]
	v_mfma_f32_16x16x32_bf16 v[116:119], v[174:177], v[182:185], v[116:119]
	v_mfma_f32_16x16x32_bf16 v[108:111], v[166:169], v[206:209], v[108:111]
	v_mfma_f32_16x16x32_bf16 v[100:103], v[174:177], v[206:209], v[100:103]
	v_mfma_f32_16x16x32_bf16 v[88:91], v[166:169], v[214:217], v[88:91]
	v_mfma_f32_16x16x32_bf16 v[80:83], v[174:177], v[214:217], v[80:83]
	v_mfma_f32_16x16x32_bf16 v[72:75], v[166:169], v[222:225], v[72:75]
	v_mfma_f32_16x16x32_bf16 v[64:67], v[174:177], v[222:225], v[64:67]
	s_barrier
	s_setprio 0
	s_add_i32 s30, s76, s56
	s_add_u32 s100, s36, 0x80
	s_addc_u32 s101, s37, 0
	s_mov_b32 m0, s30
	ds_read_b128 v[178:181], v149 offset:49152
	ds_read_b128 v[182:185], v149 offset:50176
	ds_read_b128 v[202:205], v149 offset:51200
	ds_read_b128 v[206:209], v149 offset:52224
	ds_read_b128 v[210:213], v149 offset:53248
	ds_read_b128 v[214:217], v149 offset:54272
	ds_read_b128 v[218:221], v149 offset:55296
	ds_read_b128 v[222:225], v149 offset:56320
	global_load_lds_dwordx4 v188, s[100:101]
	s_add_i32 m0, s30, 0x2000
	s_add_u32 s30, s36, 0x40080
	s_addc_u32 s31, s37, 0
	s_add_i32 s36, s77, s56
	global_load_lds_dwordx4 v132, s[100:101]
	s_mov_b32 m0, s36
	s_nop 0
	global_load_lds_dwordx4 v188, s[30:31]
	s_add_i32 m0, s36, 0x2000
	s_nop 0
	global_load_lds_dwordx4 v132, s[30:31]
	s_add_u32 s100, s38, 0x80
	s_addc_u32 s101, s39, 0
	s_mov_b32 m0, s90
	s_nop 0
	global_load_lds_dwordx4 v136, s[100:101]
	s_mov_b32 m0, s91
	s_nop 0
	global_load_lds_dwordx4 v134, s[100:101]
	s_waitcnt vmcnt(8)
	s_waitcnt lgkmcnt(0)
	s_setprio 1
	s_barrier
	v_mfma_f32_16x16x32_bf16 v[60:63], v[96:99], v[178:181], v[60:63]
	v_mfma_f32_16x16x32_bf16 v[52:55], v[154:157], v[178:181], v[52:55]
	v_mfma_f32_16x16x32_bf16 v[44:47], v[96:99], v[202:205], v[44:47]
	v_mfma_f32_16x16x32_bf16 v[36:39], v[154:157], v[202:205], v[36:39]
	v_mfma_f32_16x16x32_bf16 v[28:31], v[96:99], v[210:213], v[28:31]
	v_mfma_f32_16x16x32_bf16 v[20:23], v[154:157], v[210:213], v[20:23]
	v_mfma_f32_16x16x32_bf16 v[12:15], v[96:99], v[218:221], v[12:15]
	v_mfma_f32_16x16x32_bf16 v[4:7], v[154:157], v[218:221], v[4:7]
	v_mfma_f32_16x16x32_bf16 v[60:63], v[150:153], v[182:185], v[60:63]
	v_mfma_f32_16x16x32_bf16 v[52:55], v[158:161], v[182:185], v[52:55]
	v_mfma_f32_16x16x32_bf16 v[44:47], v[150:153], v[206:209], v[44:47]
	v_mfma_f32_16x16x32_bf16 v[36:39], v[158:161], v[206:209], v[36:39]
	v_mfma_f32_16x16x32_bf16 v[28:31], v[150:153], v[214:217], v[28:31]
	v_mfma_f32_16x16x32_bf16 v[20:23], v[158:161], v[214:217], v[20:23]
	v_mfma_f32_16x16x32_bf16 v[12:15], v[150:153], v[222:225], v[12:15]
	v_mfma_f32_16x16x32_bf16 v[4:7], v[158:161], v[222:225], v[4:7]
	v_mfma_f32_16x16x32_bf16 v[56:59], v[162:165], v[178:181], v[56:59]
	v_mfma_f32_16x16x32_bf16 v[48:51], v[170:173], v[178:181], v[48:51]
	v_mfma_f32_16x16x32_bf16 v[40:43], v[162:165], v[202:205], v[40:43]
	v_mfma_f32_16x16x32_bf16 v[32:35], v[170:173], v[202:205], v[32:35]
	v_mfma_f32_16x16x32_bf16 v[24:27], v[162:165], v[210:213], v[24:27]
	v_mfma_f32_16x16x32_bf16 v[16:19], v[170:173], v[210:213], v[16:19]
	v_mfma_f32_16x16x32_bf16 v[8:11], v[162:165], v[218:221], v[8:11]
	v_mfma_f32_16x16x32_bf16 v[0:3], v[170:173], v[218:221], v[0:3]
	v_mfma_f32_16x16x32_bf16 v[56:59], v[166:169], v[182:185], v[56:59]
	v_mfma_f32_16x16x32_bf16 v[48:51], v[174:177], v[182:185], v[48:51]
	v_mfma_f32_16x16x32_bf16 v[40:43], v[166:169], v[206:209], v[40:43]
	v_mfma_f32_16x16x32_bf16 v[32:35], v[174:177], v[206:209], v[32:35]
	v_mfma_f32_16x16x32_bf16 v[24:27], v[166:169], v[214:217], v[24:27]
	v_mfma_f32_16x16x32_bf16 v[16:19], v[174:177], v[214:217], v[16:19]
	v_mfma_f32_16x16x32_bf16 v[8:11], v[166:169], v[222:225], v[8:11]
	v_mfma_f32_16x16x32_bf16 v[0:3], v[174:177], v[222:225], v[0:3]
	s_barrier
	s_setprio 0
	s_add_i32 s43, s43, 2
	s_cmp_gt_u32 s43, 13
	s_mov_b64 s[30:31], s[34:35]
	s_cbranch_scc1 .Lpeel_exit_swiglu
.LBB0_528:
	s_add_u32 s34, s30, 0x100
	s_addc_u32 s35, s31, 0
	s_add_u32 s38, s30, 0xfffff900
	s_addc_u32 s39, s31, -1
	s_cmp_gt_u32 s34, 0x7ff
	s_cselect_b32 s34, s38, s34
	s_cselect_b32 s35, s39, s35
	s_add_u32 s36, s28, s34
	s_addc_u32 s37, s29, s35
	s_add_u32 s76, s26, s34
	s_addc_u32 s77, s27, s35
	s_add_i32 s86, 0, 0x10000
	s_cmp_eq_u32 s43, 12
	s_cselect_b32 s39, s19, s37
	s_cselect_b32 s38, s25, s36
	s_cselect_b32 s37, s0, s77
	s_cselect_b32 s36, s17, s76
	s_add_i32 s76, 0, 0x14000
	ds_read_b128 v[96:99], v186
	ds_read_b128 v[150:153], v186 offset:1024
	ds_read_b128 v[154:157], v186 offset:2048
	ds_read_b128 v[158:161], v186 offset:3072
	ds_read_b128 v[162:165], v186 offset:16384
	ds_read_b128 v[166:169], v186 offset:17408
	ds_read_b128 v[170:173], v186 offset:18432
	ds_read_b128 v[174:177], v186 offset:19456
	s_add_u32 s30, s28, s30
	s_addc_u32 s31, s29, s31
	s_add_u32 s30, s30, 0x40080
	s_addc_u32 s31, s31, 0
	s_add_i32 m0, s60, 0xc000
	ds_read_b128 v[178:181], v149
	ds_read_b128 v[182:185], v149 offset:1024
	ds_read_b128 v[202:205], v149 offset:2048
	ds_read_b128 v[206:209], v149 offset:3072
	ds_read_b128 v[210:213], v149 offset:4096
	ds_read_b128 v[214:217], v149 offset:5120
	ds_read_b128 v[218:221], v149 offset:6144
	ds_read_b128 v[222:225], v149 offset:7168
	global_load_lds_dwordx4 v136, s[30:31]
	s_add_i32 m0, s60, 0xe000
	s_nop 0
	global_load_lds_dwordx4 v134, s[30:31]
	s_waitcnt vmcnt(8)
	s_waitcnt lgkmcnt(0)
	s_setprio 1
	s_barrier
	v_mfma_f32_16x16x32_bf16 v[128:131], v[96:99], v[178:181], v[128:131]
	v_mfma_f32_16x16x32_bf16 v[120:123], v[154:157], v[178:181], v[120:123]
	v_mfma_f32_16x16x32_bf16 v[112:115], v[96:99], v[202:205], v[112:115]
	v_mfma_f32_16x16x32_bf16 v[104:107], v[154:157], v[202:205], v[104:107]
	v_mfma_f32_16x16x32_bf16 v[92:95], v[96:99], v[210:213], v[92:95]
	v_mfma_f32_16x16x32_bf16 v[84:87], v[154:157], v[210:213], v[84:87]
	v_mfma_f32_16x16x32_bf16 v[76:79], v[96:99], v[218:221], v[76:79]
	v_mfma_f32_16x16x32_bf16 v[68:71], v[154:157], v[218:221], v[68:71]
	v_mfma_f32_16x16x32_bf16 v[128:131], v[150:153], v[182:185], v[128:131]
	v_mfma_f32_16x16x32_bf16 v[120:123], v[158:161], v[182:185], v[120:123]
	v_mfma_f32_16x16x32_bf16 v[112:115], v[150:153], v[206:209], v[112:115]
	v_mfma_f32_16x16x32_bf16 v[104:107], v[158:161], v[206:209], v[104:107]
	v_mfma_f32_16x16x32_bf16 v[92:95], v[150:153], v[214:217], v[92:95]
	v_mfma_f32_16x16x32_bf16 v[84:87], v[158:161], v[214:217], v[84:87]
	v_mfma_f32_16x16x32_bf16 v[76:79], v[150:153], v[222:225], v[76:79]
	v_mfma_f32_16x16x32_bf16 v[68:71], v[158:161], v[222:225], v[68:71]
	v_mfma_f32_16x16x32_bf16 v[124:127], v[162:165], v[178:181], v[124:127]
	v_mfma_f32_16x16x32_bf16 v[116:119], v[170:173], v[178:181], v[116:119]
	v_mfma_f32_16x16x32_bf16 v[108:111], v[162:165], v[202:205], v[108:111]
	v_mfma_f32_16x16x32_bf16 v[100:103], v[170:173], v[202:205], v[100:103]
	v_mfma_f32_16x16x32_bf16 v[88:91], v[162:165], v[210:213], v[88:91]
	v_mfma_f32_16x16x32_bf16 v[80:83], v[170:173], v[210:213], v[80:83]
	v_mfma_f32_16x16x32_bf16 v[72:75], v[162:165], v[218:221], v[72:75]
	v_mfma_f32_16x16x32_bf16 v[64:67], v[170:173], v[218:221], v[64:67]
	v_mfma_f32_16x16x32_bf16 v[124:127], v[166:169], v[182:185], v[124:127]
	v_mfma_f32_16x16x32_bf16 v[116:119], v[174:177], v[182:185], v[116:119]
	v_mfma_f32_16x16x32_bf16 v[108:111], v[166:169], v[206:209], v[108:111]
	v_mfma_f32_16x16x32_bf16 v[100:103], v[174:177], v[206:209], v[100:103]
	v_mfma_f32_16x16x32_bf16 v[88:91], v[166:169], v[214:217], v[88:91]
	v_mfma_f32_16x16x32_bf16 v[80:83], v[174:177], v[214:217], v[80:83]
	v_mfma_f32_16x16x32_bf16 v[72:75], v[166:169], v[222:225], v[72:75]
	v_mfma_f32_16x16x32_bf16 v[64:67], v[174:177], v[222:225], v[64:67]
	s_barrier
	s_setprio 0
	s_add_i32 s30, s86, s56
	s_mov_b32 m0, s30
	ds_read_b128 v[178:181], v149 offset:16384
	ds_read_b128 v[182:185], v149 offset:17408
	ds_read_b128 v[202:205], v149 offset:18432
	ds_read_b128 v[206:209], v149 offset:19456
	ds_read_b128 v[210:213], v149 offset:20480
	ds_read_b128 v[214:217], v149 offset:21504
	ds_read_b128 v[218:221], v149 offset:22528
	ds_read_b128 v[222:225], v149 offset:23552
	global_load_lds_dwordx4 v188, s[36:37]
	s_add_i32 m0, s30, 0x2000
	s_add_u32 s30, s36, 0x40000
	s_addc_u32 s31, s37, 0
	s_add_i32 s76, s76, s56
	global_load_lds_dwordx4 v132, s[36:37]
	s_mov_b32 m0, s76
	s_nop 0
	global_load_lds_dwordx4 v188, s[30:31]
	s_add_i32 m0, s76, 0x2000
	s_nop 0
	global_load_lds_dwordx4 v132, s[30:31]
	s_mov_b32 m0, s60
	s_nop 0
	global_load_lds_dwordx4 v136, s[38:39]
	s_mov_b32 m0, s71
	s_nop 0
	global_load_lds_dwordx4 v134, s[38:39]
	s_waitcnt vmcnt(8)
	s_waitcnt lgkmcnt(0)
	s_setprio 1
	s_barrier
	v_mfma_f32_16x16x32_bf16 v[60:63], v[96:99], v[178:181], v[60:63]
	v_mfma_f32_16x16x32_bf16 v[52:55], v[154:157], v[178:181], v[52:55]
	v_mfma_f32_16x16x32_bf16 v[44:47], v[96:99], v[202:205], v[44:47]
	v_mfma_f32_16x16x32_bf16 v[36:39], v[154:157], v[202:205], v[36:39]
	v_mfma_f32_16x16x32_bf16 v[28:31], v[96:99], v[210:213], v[28:31]
	v_mfma_f32_16x16x32_bf16 v[20:23], v[154:157], v[210:213], v[20:23]
	v_mfma_f32_16x16x32_bf16 v[12:15], v[96:99], v[218:221], v[12:15]
	v_mfma_f32_16x16x32_bf16 v[4:7], v[154:157], v[218:221], v[4:7]
	v_mfma_f32_16x16x32_bf16 v[60:63], v[150:153], v[182:185], v[60:63]
	v_mfma_f32_16x16x32_bf16 v[52:55], v[158:161], v[182:185], v[52:55]
	v_mfma_f32_16x16x32_bf16 v[44:47], v[150:153], v[206:209], v[44:47]
	v_mfma_f32_16x16x32_bf16 v[36:39], v[158:161], v[206:209], v[36:39]
	v_mfma_f32_16x16x32_bf16 v[28:31], v[150:153], v[214:217], v[28:31]
	v_mfma_f32_16x16x32_bf16 v[20:23], v[158:161], v[214:217], v[20:23]
	v_mfma_f32_16x16x32_bf16 v[12:15], v[150:153], v[222:225], v[12:15]
	v_mfma_f32_16x16x32_bf16 v[4:7], v[158:161], v[222:225], v[4:7]
	v_mfma_f32_16x16x32_bf16 v[56:59], v[162:165], v[178:181], v[56:59]
	v_mfma_f32_16x16x32_bf16 v[48:51], v[170:173], v[178:181], v[48:51]
	v_mfma_f32_16x16x32_bf16 v[40:43], v[162:165], v[202:205], v[40:43]
	v_mfma_f32_16x16x32_bf16 v[32:35], v[170:173], v[202:205], v[32:35]
	v_mfma_f32_16x16x32_bf16 v[24:27], v[162:165], v[210:213], v[24:27]
	v_mfma_f32_16x16x32_bf16 v[16:19], v[170:173], v[210:213], v[16:19]
	v_mfma_f32_16x16x32_bf16 v[8:11], v[162:165], v[218:221], v[8:11]
	v_mfma_f32_16x16x32_bf16 v[0:3], v[170:173], v[218:221], v[0:3]
	v_mfma_f32_16x16x32_bf16 v[56:59], v[166:169], v[182:185], v[56:59]
	v_mfma_f32_16x16x32_bf16 v[48:51], v[174:177], v[182:185], v[48:51]
	v_mfma_f32_16x16x32_bf16 v[40:43], v[166:169], v[206:209], v[40:43]
	v_mfma_f32_16x16x32_bf16 v[32:35], v[174:177], v[206:209], v[32:35]
	v_mfma_f32_16x16x32_bf16 v[24:27], v[166:169], v[214:217], v[24:27]
	v_mfma_f32_16x16x32_bf16 v[16:19], v[174:177], v[214:217], v[16:19]
	v_mfma_f32_16x16x32_bf16 v[8:11], v[166:169], v[222:225], v[8:11]
	v_mfma_f32_16x16x32_bf16 v[0:3], v[174:177], v[222:225], v[0:3]
	s_barrier
	s_setprio 0
	s_add_i32 s76, 0, 0x18000
	s_add_i32 s77, 0, 0x1c000
	ds_read_b128 v[96:99], v186 offset:32768
	ds_read_b128 v[150:153], v186 offset:33792
	ds_read_b128 v[154:157], v186 offset:34816
	ds_read_b128 v[158:161], v186 offset:35840
	ds_read_b128 v[162:165], v186 offset:49152
	ds_read_b128 v[166:169], v186 offset:50176
	ds_read_b128 v[170:173], v186 offset:51200
	ds_read_b128 v[174:177], v186 offset:52224
	s_add_u32 s30, s38, 0x40000
	s_addc_u32 s31, s39, 0
	s_mov_b32 m0, s87
	ds_read_b128 v[178:181], v149 offset:32768
	ds_read_b128 v[182:185], v149 offset:33792
	ds_read_b128 v[202:205], v149 offset:34816
	ds_read_b128 v[206:209], v149 offset:35840
	ds_read_b128 v[210:213], v149 offset:36864
	ds_read_b128 v[214:217], v149 offset:37888
	ds_read_b128 v[218:221], v149 offset:38912
	ds_read_b128 v[222:225], v149 offset:39936
	global_load_lds_dwordx4 v136, s[30:31]
	s_mov_b32 m0, s89
	s_nop 0
	global_load_lds_dwordx4 v134, s[30:31]
	s_waitcnt vmcnt(8)
	s_waitcnt lgkmcnt(0)
	s_setprio 1
	s_barrier
	v_mfma_f32_16x16x32_bf16 v[128:131], v[96:99], v[178:181], v[128:131]
	v_mfma_f32_16x16x32_bf16 v[120:123], v[154:157], v[178:181], v[120:123]
	v_mfma_f32_16x16x32_bf16 v[112:115], v[96:99], v[202:205], v[112:115]
	v_mfma_f32_16x16x32_bf16 v[104:107], v[154:157], v[202:205], v[104:107]
	v_mfma_f32_16x16x32_bf16 v[92:95], v[96:99], v[210:213], v[92:95]
	v_mfma_f32_16x16x32_bf16 v[84:87], v[154:157], v[210:213], v[84:87]
	v_mfma_f32_16x16x32_bf16 v[76:79], v[96:99], v[218:221], v[76:79]
	v_mfma_f32_16x16x32_bf16 v[68:71], v[154:157], v[218:221], v[68:71]
	v_mfma_f32_16x16x32_bf16 v[128:131], v[150:153], v[182:185], v[128:131]
	v_mfma_f32_16x16x32_bf16 v[120:123], v[158:161], v[182:185], v[120:123]
	v_mfma_f32_16x16x32_bf16 v[112:115], v[150:153], v[206:209], v[112:115]
	v_mfma_f32_16x16x32_bf16 v[104:107], v[158:161], v[206:209], v[104:107]
	v_mfma_f32_16x16x32_bf16 v[92:95], v[150:153], v[214:217], v[92:95]
	v_mfma_f32_16x16x32_bf16 v[84:87], v[158:161], v[214:217], v[84:87]
	v_mfma_f32_16x16x32_bf16 v[76:79], v[150:153], v[222:225], v[76:79]
	v_mfma_f32_16x16x32_bf16 v[68:71], v[158:161], v[222:225], v[68:71]
	v_mfma_f32_16x16x32_bf16 v[124:127], v[162:165], v[178:181], v[124:127]
	v_mfma_f32_16x16x32_bf16 v[116:119], v[170:173], v[178:181], v[116:119]
	v_mfma_f32_16x16x32_bf16 v[108:111], v[162:165], v[202:205], v[108:111]
	v_mfma_f32_16x16x32_bf16 v[100:103], v[170:173], v[202:205], v[100:103]
	v_mfma_f32_16x16x32_bf16 v[88:91], v[162:165], v[210:213], v[88:91]
	v_mfma_f32_16x16x32_bf16 v[80:83], v[170:173], v[210:213], v[80:83]
	v_mfma_f32_16x16x32_bf16 v[72:75], v[162:165], v[218:221], v[72:75]
	v_mfma_f32_16x16x32_bf16 v[64:67], v[170:173], v[218:221], v[64:67]
	v_mfma_f32_16x16x32_bf16 v[124:127], v[166:169], v[182:185], v[124:127]
	v_mfma_f32_16x16x32_bf16 v[116:119], v[174:177], v[182:185], v[116:119]
	v_mfma_f32_16x16x32_bf16 v[108:111], v[166:169], v[206:209], v[108:111]
	v_mfma_f32_16x16x32_bf16 v[100:103], v[174:177], v[206:209], v[100:103]
	v_mfma_f32_16x16x32_bf16 v[88:91], v[166:169], v[214:217], v[88:91]
	v_mfma_f32_16x16x32_bf16 v[80:83], v[174:177], v[214:217], v[80:83]
	v_mfma_f32_16x16x32_bf16 v[72:75], v[166:169], v[222:225], v[72:75]
	v_mfma_f32_16x16x32_bf16 v[64:67], v[174:177], v[222:225], v[64:67]
	s_barrier
	s_setprio 0
	s_add_i32 s30, s76, s56
	s_add_u32 s100, s36, 0x80
	s_addc_u32 s101, s37, 0
	s_mov_b32 m0, s30
	ds_read_b128 v[178:181], v149 offset:49152
	ds_read_b128 v[182:185], v149 offset:50176
	ds_read_b128 v[202:205], v149 offset:51200
	ds_read_b128 v[206:209], v149 offset:52224
	ds_read_b128 v[210:213], v149 offset:53248
	ds_read_b128 v[214:217], v149 offset:54272
	ds_read_b128 v[218:221], v149 offset:55296
	ds_read_b128 v[222:225], v149 offset:56320
	global_load_lds_dwordx4 v188, s[100:101]
	s_add_i32 m0, s30, 0x2000
	s_add_u32 s30, s36, 0x40080
	s_addc_u32 s31, s37, 0
	s_add_i32 s36, s77, s56
	global_load_lds_dwordx4 v132, s[100:101]
	s_mov_b32 m0, s36
	s_nop 0
	global_load_lds_dwordx4 v188, s[30:31]
	s_add_i32 m0, s36, 0x2000
	s_nop 0
	global_load_lds_dwordx4 v132, s[30:31]
	s_add_u32 s100, s38, 0x80
	s_addc_u32 s101, s39, 0
	s_mov_b32 m0, s90
	s_nop 0
	global_load_lds_dwordx4 v136, s[100:101]
	s_mov_b32 m0, s91
	s_nop 0
	global_load_lds_dwordx4 v134, s[100:101]
	s_waitcnt vmcnt(8)
	s_waitcnt lgkmcnt(0)
	s_setprio 1
	s_barrier
	v_mfma_f32_16x16x32_bf16 v[60:63], v[96:99], v[178:181], v[60:63]
	v_mfma_f32_16x16x32_bf16 v[52:55], v[154:157], v[178:181], v[52:55]
	v_mfma_f32_16x16x32_bf16 v[44:47], v[96:99], v[202:205], v[44:47]
	v_mfma_f32_16x16x32_bf16 v[36:39], v[154:157], v[202:205], v[36:39]
	v_mfma_f32_16x16x32_bf16 v[28:31], v[96:99], v[210:213], v[28:31]
	v_mfma_f32_16x16x32_bf16 v[20:23], v[154:157], v[210:213], v[20:23]
	v_mfma_f32_16x16x32_bf16 v[12:15], v[96:99], v[218:221], v[12:15]
	v_mfma_f32_16x16x32_bf16 v[4:7], v[154:157], v[218:221], v[4:7]
	v_mfma_f32_16x16x32_bf16 v[60:63], v[150:153], v[182:185], v[60:63]
	v_mfma_f32_16x16x32_bf16 v[52:55], v[158:161], v[182:185], v[52:55]
	v_mfma_f32_16x16x32_bf16 v[44:47], v[150:153], v[206:209], v[44:47]
	v_mfma_f32_16x16x32_bf16 v[36:39], v[158:161], v[206:209], v[36:39]
	v_mfma_f32_16x16x32_bf16 v[28:31], v[150:153], v[214:217], v[28:31]
	v_mfma_f32_16x16x32_bf16 v[20:23], v[158:161], v[214:217], v[20:23]
	v_mfma_f32_16x16x32_bf16 v[12:15], v[150:153], v[222:225], v[12:15]
	v_mfma_f32_16x16x32_bf16 v[4:7], v[158:161], v[222:225], v[4:7]
	v_mfma_f32_16x16x32_bf16 v[56:59], v[162:165], v[178:181], v[56:59]
	v_mfma_f32_16x16x32_bf16 v[48:51], v[170:173], v[178:181], v[48:51]
	v_mfma_f32_16x16x32_bf16 v[40:43], v[162:165], v[202:205], v[40:43]
	v_mfma_f32_16x16x32_bf16 v[32:35], v[170:173], v[202:205], v[32:35]
	v_mfma_f32_16x16x32_bf16 v[24:27], v[162:165], v[210:213], v[24:27]
	v_mfma_f32_16x16x32_bf16 v[16:19], v[170:173], v[210:213], v[16:19]
	v_mfma_f32_16x16x32_bf16 v[8:11], v[162:165], v[218:221], v[8:11]
	v_mfma_f32_16x16x32_bf16 v[0:3], v[170:173], v[218:221], v[0:3]
	v_mfma_f32_16x16x32_bf16 v[56:59], v[166:169], v[182:185], v[56:59]
	v_mfma_f32_16x16x32_bf16 v[48:51], v[174:177], v[182:185], v[48:51]
	v_mfma_f32_16x16x32_bf16 v[40:43], v[166:169], v[206:209], v[40:43]
	v_mfma_f32_16x16x32_bf16 v[32:35], v[174:177], v[206:209], v[32:35]
	v_mfma_f32_16x16x32_bf16 v[24:27], v[166:169], v[214:217], v[24:27]
	v_mfma_f32_16x16x32_bf16 v[16:19], v[174:177], v[214:217], v[16:19]
	v_mfma_f32_16x16x32_bf16 v[8:11], v[166:169], v[222:225], v[8:11]
	v_mfma_f32_16x16x32_bf16 v[0:3], v[174:177], v[222:225], v[0:3]
	s_barrier
	s_setprio 0
	s_add_i32 s43, s43, 2
	s_cmp_gt_u32 s43, 13
	s_mov_b64 s[30:31], s[34:35]
	s_cbranch_scc0 .LBB0_528
